# adds: delete the 24 redundant compiler lgkmcnt(0) waits after the barrier in the six GEMM k-loops
# speedup vs baseline: 1.0086x; 1.0086x over previous
; #define PG8_STAGE(bufoff, gbase, voff) do { _Pragma("unroll") for (int _i = 0; _i < 2; ++_i) \
;         __builtin_amdgcn_global_load_lds((const unsigned*)((const char*)(gbase) + (voff)[_i]), (LAS unsigned*)(lds + (bufoff) + ldsw + _i * 8192), 16, 0, 0); } while (0)
; #define PG8_LDA(dst, b, h) do { _Pragma("unroll") for (int m = 0; m < 4; ++m) _Pragma("unroll") for (int k = 0; k < 2; ++k) dst[m][k] = *(const LAS bf16x8*)(lds + PG8_SA(b, h) + aoff + m * 2048 + k * 1024); } while (0)
; #define PG8_MMA(ai, bj, At, Bt) do { __builtin_amdgcn_s_setprio(1); _Pragma("unroll") for (int m = 0; m < 4; ++m) _Pragma("unroll") for (int n = 0; n < 2; ++n) _Pragma("unroll") for (int k = 0; k < 2; ++k) \
;         acc[ai][bj][m][n] = __builtin_amdgcn_mfma_f32_16x16x32_bf16(Bt[n][k], At[m][k], acc[ai][bj][m][n], 0, 0, 0); __builtin_amdgcn_s_setprio(0); } while (0)
; #define PG8_WAIT_V(n) asm volatile("s_waitcnt vmcnt(" #n ")" ::: "memory")
; #define PG8_WAIT_L(n) asm volatile("s_waitcnt lgkmcnt(" #n ")" ::: "memory")
; #define PG8_BAR __builtin_amdgcn_s_barrier()
; #define PG8_SCHED __builtin_amdgcn_sched_barrier(0)
; template <class Epi, class Sched, int NSEG, int KK, int LDA, int LDB>
; __device__ __forceinline__ void gemm_phase(LAS unsigned char* lds, const Gemm g, const Sched& S, const Epi& E) {
;     ...
;             PG8_WAIT_V(8); PG8_WAIT_L(0); PG8_BAR; PG8_MMA(0, 0, At, B0); PG8_MMA(0, 1, At, B1); PG8_BAR; PG8_SCHED;
;             PG8_LDA(At, 0, 1); PG8_STAGE(PG8_SB(0, 0), b2, voffB); PG8_STAGE(PG8_SB(0, 1), b2 + hstepB, voffB); PG8_STAGE(PG8_SA(0, 0), a2, voffA);
;             PG8_WAIT_V(8); PG8_WAIT_L(0); PG8_BAR; PG8_MMA(1, 0, At, B0); PG8_MMA(1, 1, At, B1); PG8_BAR; PG8_SCHED;
.Lskw_0_1:
	s_waitcnt lgkmcnt(0)
	s_barrier
	s_setprio 1
	v_mfma_f32_16x16x32_bf16 v[126:129], v[130:133], v[188:191], v[126:129]
	v_mfma_f32_16x16x32_bf16 v[122:125], v[138:141], v[188:191], v[122:125]
	v_mfma_f32_16x16x32_bf16 v[110:113], v[130:133], v[196:199], v[110:113]
	v_mfma_f32_16x16x32_bf16 v[106:109], v[138:141], v[196:199], v[106:109]
	v_mfma_f32_16x16x32_bf16 v[94:97], v[130:133], v[204:207], v[94:97]
	v_mfma_f32_16x16x32_bf16 v[90:93], v[138:141], v[204:207], v[90:93]
	v_mfma_f32_16x16x32_bf16 v[78:81], v[130:133], v[212:215], v[78:81]
	v_mfma_f32_16x16x32_bf16 v[74:77], v[138:141], v[212:215], v[74:77]
	v_mfma_f32_16x16x32_bf16 v[126:129], v[134:137], v[192:195], v[126:129]
	v_mfma_f32_16x16x32_bf16 v[122:125], v[158:161], v[192:195], v[122:125]
	v_mfma_f32_16x16x32_bf16 v[110:113], v[134:137], v[200:203], v[110:113]
	v_mfma_f32_16x16x32_bf16 v[106:109], v[158:161], v[200:203], v[106:109]
	v_mfma_f32_16x16x32_bf16 v[94:97], v[134:137], v[208:211], v[94:97]
	v_mfma_f32_16x16x32_bf16 v[90:93], v[158:161], v[208:211], v[90:93]
	v_mfma_f32_16x16x32_bf16 v[78:81], v[134:137], v[216:219], v[78:81]
	v_mfma_f32_16x16x32_bf16 v[74:77], v[158:161], v[216:219], v[74:77]
	s_setprio 0
	s_setprio 1
	v_mfma_f32_16x16x32_bf16 v[118:121], v[162:165], v[188:191], v[118:121]
	v_mfma_f32_16x16x32_bf16 v[114:117], v[180:183], v[188:191], v[114:117]
	v_mfma_f32_16x16x32_bf16 v[102:105], v[162:165], v[196:199], v[102:105]
	v_mfma_f32_16x16x32_bf16 v[98:101], v[180:183], v[196:199], v[98:101]
	v_mfma_f32_16x16x32_bf16 v[86:89], v[162:165], v[204:207], v[86:89]
	v_mfma_f32_16x16x32_bf16 v[82:85], v[180:183], v[204:207], v[82:85]
	v_mfma_f32_16x16x32_bf16 v[70:73], v[162:165], v[212:215], v[70:73]
	v_mfma_f32_16x16x32_bf16 v[66:69], v[180:183], v[212:215], v[66:69]
	v_mfma_f32_16x16x32_bf16 v[118:121], v[176:179], v[192:195], v[118:121]
	v_mfma_f32_16x16x32_bf16 v[114:117], v[184:187], v[192:195], v[114:117]
	v_mfma_f32_16x16x32_bf16 v[102:105], v[176:179], v[200:203], v[102:105]
	v_mfma_f32_16x16x32_bf16 v[98:101], v[184:187], v[200:203], v[98:101]
	v_mfma_f32_16x16x32_bf16 v[86:89], v[176:179], v[208:211], v[86:89]
	v_mfma_f32_16x16x32_bf16 v[82:85], v[184:187], v[208:211], v[82:85]
	v_mfma_f32_16x16x32_bf16 v[70:73], v[176:179], v[216:219], v[70:73]
	v_mfma_f32_16x16x32_bf16 v[66:69], v[184:187], v[216:219], v[66:69]
	s_setprio 0
	s_barrier
	s_add_i32 s63, s63, s13
	v_lshl_add_u64 v[154:155], s[10:11], 0, v[146:147]
	s_mov_b32 m0, s63
	ds_read_b128 v[188:191], v157 offset:16384
	ds_read_b128 v[192:195], v157 offset:17408
	ds_read_b128 v[196:199], v157 offset:18432
	ds_read_b128 v[200:203], v157 offset:19456
	ds_read_b128 v[204:207], v157 offset:20480
	ds_read_b128 v[208:211], v157 offset:21504
	ds_read_b128 v[212:215], v157 offset:22528
	ds_read_b128 v[216:219], v157 offset:23552
	global_load_lds_dwordx4 v[154:155], off
	s_add_i32 m0, s63, 0x2000
	s_add_u32 s94, s10, 0x40000
	v_lshl_add_u64 v[166:167], s[10:11], 0, v[142:143]
	s_addc_u32 s95, s11, 0
	s_add_i32 s63, s77, s13
	global_load_lds_dwordx4 v[166:167], off
	v_lshl_add_u64 v[220:221], s[94:95], 0, v[146:147]
	s_mov_b32 m0, s63
	v_lshl_add_u64 v[222:223], s[50:51], 0, v[144:145]
	global_load_lds_dwordx4 v[220:221], off
	v_lshl_add_u64 v[220:221], s[94:95], 0, v[142:143]
	s_add_i32 m0, s63, 0x2000
	s_nop 0
	global_load_lds_dwordx4 v[220:221], off
	v_lshl_add_u64 v[220:221], s[50:51], 0, v[148:149]
	s_mov_b32 m0, s22
	s_nop 0
	global_load_lds_dwordx4 v[220:221], off
	s_mov_b32 m0, s23
	s_nop 0
	global_load_lds_dwordx4 v[222:223], off
	s_cmp_lg_u32 s101, 0
	s_cbranch_scc1 .Lskw_0_2
	s_waitcnt vmcnt(8)
.Lskw_0_2:
	s_mov_b32 s101, 0
	s_waitcnt lgkmcnt(0)
	s_barrier
	s_setprio 1
	v_mfma_f32_16x16x32_bf16 v[62:65], v[130:133], v[188:191], v[62:65]
	v_mfma_f32_16x16x32_bf16 v[58:61], v[138:141], v[188:191], v[58:61]
	v_mfma_f32_16x16x32_bf16 v[46:49], v[130:133], v[196:199], v[46:49]
	v_mfma_f32_16x16x32_bf16 v[42:45], v[138:141], v[196:199], v[42:45]
	v_mfma_f32_16x16x32_bf16 v[30:33], v[130:133], v[204:207], v[30:33]
	v_mfma_f32_16x16x32_bf16 v[26:29], v[138:141], v[204:207], v[26:29]
	v_mfma_f32_16x16x32_bf16 v[14:17], v[130:133], v[212:215], v[14:17]
	v_mfma_f32_16x16x32_bf16 v[10:13], v[138:141], v[212:215], v[10:13]
	v_mfma_f32_16x16x32_bf16 v[62:65], v[134:137], v[192:195], v[62:65]
	v_mfma_f32_16x16x32_bf16 v[58:61], v[158:161], v[192:195], v[58:61]
	v_mfma_f32_16x16x32_bf16 v[46:49], v[134:137], v[200:203], v[46:49]
	v_mfma_f32_16x16x32_bf16 v[42:45], v[158:161], v[200:203], v[42:45]
	v_mfma_f32_16x16x32_bf16 v[30:33], v[134:137], v[208:211], v[30:33]
	v_mfma_f32_16x16x32_bf16 v[26:29], v[158:161], v[208:211], v[26:29]
	v_mfma_f32_16x16x32_bf16 v[14:17], v[134:137], v[216:219], v[14:17]
	v_mfma_f32_16x16x32_bf16 v[10:13], v[158:161], v[216:219], v[10:13]
	s_setprio 0
	s_setprio 1
	v_mfma_f32_16x16x32_bf16 v[54:57], v[162:165], v[188:191], v[54:57]
	v_mfma_f32_16x16x32_bf16 v[50:53], v[180:183], v[188:191], v[50:53]
	v_mfma_f32_16x16x32_bf16 v[38:41], v[162:165], v[196:199], v[38:41]
	v_mfma_f32_16x16x32_bf16 v[34:37], v[180:183], v[196:199], v[34:37]
	v_mfma_f32_16x16x32_bf16 v[22:25], v[162:165], v[204:207], v[22:25]
	v_mfma_f32_16x16x32_bf16 v[18:21], v[180:183], v[204:207], v[18:21]
	v_mfma_f32_16x16x32_bf16 v[6:9], v[162:165], v[212:215], v[6:9]
	v_mfma_f32_16x16x32_bf16 v[2:5], v[180:183], v[212:215], v[2:5]
	v_mfma_f32_16x16x32_bf16 v[54:57], v[176:179], v[192:195], v[54:57]
	v_mfma_f32_16x16x32_bf16 v[50:53], v[184:187], v[192:195], v[50:53]
	v_mfma_f32_16x16x32_bf16 v[38:41], v[176:179], v[200:203], v[38:41]
	v_mfma_f32_16x16x32_bf16 v[34:37], v[184:187], v[200:203], v[34:37]
	v_mfma_f32_16x16x32_bf16 v[22:25], v[176:179], v[208:211], v[22:25]
	v_mfma_f32_16x16x32_bf16 v[18:21], v[184:187], v[208:211], v[18:21]
	v_mfma_f32_16x16x32_bf16 v[6:9], v[176:179], v[216:219], v[6:9]
	v_mfma_f32_16x16x32_bf16 v[2:5], v[184:187], v[216:219], v[2:5]
	s_setprio 0
	s_barrier
; #define PG8_STAGE(bufoff, gbase, voff) do { _Pragma("unroll") for (int _i = 0; _i < 2; ++_i) \
;         __builtin_amdgcn_global_load_lds((const unsigned*)((const char*)(gbase) + (voff)[_i]), (LAS unsigned*)(lds + (bufoff) + ldsw + _i * 8192), 16, 0, 0); } while (0)
; #define PG8_LDA(dst, b, h) do { _Pragma("unroll") for (int m = 0; m < 4; ++m) _Pragma("unroll") for (int k = 0; k < 2; ++k) dst[m][k] = *(const LAS bf16x8*)(lds + PG8_SA(b, h) + aoff + m * 2048 + k * 1024); } while (0)
; #define PG8_LDB(dst, b, h) do { _Pragma("unroll") for (int n = 0; n < 2; ++n) _Pragma("unroll") for (int k = 0; k < 2; ++k) dst[n][k] = *(const LAS bf16x8*)(lds + PG8_SB(b, h) + boff + n * 2048 + k * 1024); } while (0)
; #define PG8_MMA(ai, bj, At, Bt) do { __builtin_amdgcn_s_setprio(1); _Pragma("unroll") for (int m = 0; m < 4; ++m) _Pragma("unroll") for (int n = 0; n < 2; ++n) _Pragma("unroll") for (int k = 0; k < 2; ++k) \
;         acc[ai][bj][m][n] = __builtin_amdgcn_mfma_f32_16x16x32_bf16(Bt[n][k], At[m][k], acc[ai][bj][m][n], 0, 0, 0); __builtin_amdgcn_s_setprio(0); } while (0)
; #define PG8_WAIT_V(n) asm volatile("s_waitcnt vmcnt(" #n ")" ::: "memory")
; #define PG8_WAIT_L(n) asm volatile("s_waitcnt lgkmcnt(" #n ")" ::: "memory")
; #define PG8_BAR __builtin_amdgcn_s_barrier()
; #define PG8_SCHED __builtin_amdgcn_sched_barrier(0)
; template <class Epi, class Sched, int NSEG, int KK, int LDA, int LDB>
; __device__ __forceinline__ void gemm_phase(LAS unsigned char* lds, const Gemm g, const Sched& S, const Epi& E) {
;     ...
;             PG8_LDB(B0, 1, 0); PG8_LDB(B1, 1, 1); PG8_SCHED; PG8_LDA(At, 1, 0); PG8_STAGE(PG8_SA(0, 1), a2 + hstepA, voffA);
;             PG8_WAIT_V(8); PG8_WAIT_L(0); PG8_BAR; PG8_MMA(0, 0, At, B0); PG8_MMA(0, 1, At, B1); PG8_BAR; PG8_SCHED;
	s_add_i32 s63, 0, 0x18000
	v_add_u32_e32 v0, s63, v156
	s_add_i32 s77, 0, 0x1c000
	ds_read_b128 v[130:133], v0
	ds_read_b128 v[134:137], v0 offset:1024
	ds_read_b128 v[138:141], v0 offset:2048
	ds_read_b128 v[158:161], v0 offset:3072
	v_add_u32_e32 v0, s77, v156
	ds_read_b128 v[162:165], v0
	ds_read_b128 v[176:179], v0 offset:1024
	ds_read_b128 v[180:183], v0 offset:2048
	ds_read_b128 v[184:187], v0 offset:3072
	s_add_u32 s50, s50, 0x40000
	s_addc_u32 s51, s51, 0
	s_mov_b32 m0, s26
	v_lshl_add_u64 v[224:225], s[50:51], 0, v[148:149]
	ds_read_b128 v[188:191], v157 offset:32768
	ds_read_b128 v[192:195], v157 offset:33792
	ds_read_b128 v[196:199], v157 offset:34816
	ds_read_b128 v[200:203], v157 offset:35840
	ds_read_b128 v[204:207], v157 offset:36864
	ds_read_b128 v[208:211], v157 offset:37888
	ds_read_b128 v[212:215], v157 offset:38912
	ds_read_b128 v[216:219], v157 offset:39936
	global_load_lds_dwordx4 v[224:225], off
	v_lshl_add_u64 v[224:225], s[50:51], 0, v[144:145]
	s_mov_b32 m0, s33
	s_nop 0
	global_load_lds_dwordx4 v[224:225], off
	s_waitcnt vmcnt(8)
	s_waitcnt lgkmcnt(0)
	s_barrier
	s_setprio 1
	v_mfma_f32_16x16x32_bf16 v[126:129], v[130:133], v[188:191], v[126:129]
	v_mfma_f32_16x16x32_bf16 v[122:125], v[138:141], v[188:191], v[122:125]
	v_mfma_f32_16x16x32_bf16 v[110:113], v[130:133], v[196:199], v[110:113]
	v_mfma_f32_16x16x32_bf16 v[106:109], v[138:141], v[196:199], v[106:109]
	v_mfma_f32_16x16x32_bf16 v[94:97], v[130:133], v[204:207], v[94:97]
	v_mfma_f32_16x16x32_bf16 v[90:93], v[138:141], v[204:207], v[90:93]
	v_mfma_f32_16x16x32_bf16 v[78:81], v[130:133], v[212:215], v[78:81]
	v_mfma_f32_16x16x32_bf16 v[74:77], v[138:141], v[212:215], v[74:77]
	v_mfma_f32_16x16x32_bf16 v[126:129], v[134:137], v[192:195], v[126:129]
	v_mfma_f32_16x16x32_bf16 v[122:125], v[158:161], v[192:195], v[122:125]
	v_mfma_f32_16x16x32_bf16 v[110:113], v[134:137], v[200:203], v[110:113]
	v_mfma_f32_16x16x32_bf16 v[106:109], v[158:161], v[200:203], v[106:109]
	v_mfma_f32_16x16x32_bf16 v[94:97], v[134:137], v[208:211], v[94:97]
	v_mfma_f32_16x16x32_bf16 v[90:93], v[158:161], v[208:211], v[90:93]
	v_mfma_f32_16x16x32_bf16 v[78:81], v[134:137], v[216:219], v[78:81]
	v_mfma_f32_16x16x32_bf16 v[74:77], v[158:161], v[216:219], v[74:77]
	s_setprio 0
	s_setprio 1
	v_mfma_f32_16x16x32_bf16 v[118:121], v[162:165], v[188:191], v[118:121]
	v_mfma_f32_16x16x32_bf16 v[114:117], v[180:183], v[188:191], v[114:117]
	v_mfma_f32_16x16x32_bf16 v[102:105], v[162:165], v[196:199], v[102:105]
	v_mfma_f32_16x16x32_bf16 v[98:101], v[180:183], v[196:199], v[98:101]
	v_mfma_f32_16x16x32_bf16 v[86:89], v[162:165], v[204:207], v[86:89]
	v_mfma_f32_16x16x32_bf16 v[82:85], v[180:183], v[204:207], v[82:85]
	v_mfma_f32_16x16x32_bf16 v[70:73], v[162:165], v[212:215], v[70:73]
	v_mfma_f32_16x16x32_bf16 v[66:69], v[180:183], v[212:215], v[66:69]
	v_mfma_f32_16x16x32_bf16 v[118:121], v[176:179], v[192:195], v[118:121]
	v_mfma_f32_16x16x32_bf16 v[114:117], v[184:187], v[192:195], v[114:117]
	v_mfma_f32_16x16x32_bf16 v[102:105], v[176:179], v[200:203], v[102:105]
	v_mfma_f32_16x16x32_bf16 v[98:101], v[184:187], v[200:203], v[98:101]
	v_mfma_f32_16x16x32_bf16 v[86:89], v[176:179], v[208:211], v[86:89]
	v_mfma_f32_16x16x32_bf16 v[82:85], v[184:187], v[208:211], v[82:85]
	v_mfma_f32_16x16x32_bf16 v[70:73], v[176:179], v[216:219], v[70:73]
	v_mfma_f32_16x16x32_bf16 v[66:69], v[184:187], v[216:219], v[66:69]
	s_setprio 0
	s_barrier
; #define PG8_STAGE(bufoff, gbase, voff) do { _Pragma("unroll") for (int _i = 0; _i < 2; ++_i) \
;         __builtin_amdgcn_global_load_lds((const unsigned*)((const char*)(gbase) + (voff)[_i]), (LAS unsigned*)(lds + (bufoff) + ldsw + _i * 8192), 16, 0, 0); } while (0)
; #define PG8_LDA(dst, b, h) do { _Pragma("unroll") for (int m = 0; m < 4; ++m) _Pragma("unroll") for (int k = 0; k < 2; ++k) dst[m][k] = *(const LAS bf16x8*)(lds + PG8_SA(b, h) + aoff + m * 2048 + k * 1024); } while (0)
; #define PG8_MMA(ai, bj, At, Bt) do { __builtin_amdgcn_s_setprio(1); _Pragma("unroll") for (int m = 0; m < 4; ++m) _Pragma("unroll") for (int n = 0; n < 2; ++n) _Pragma("unroll") for (int k = 0; k < 2; ++k) \
;         acc[ai][bj][m][n] = __builtin_amdgcn_mfma_f32_16x16x32_bf16(Bt[n][k], At[m][k], acc[ai][bj][m][n], 0, 0, 0); __builtin_amdgcn_s_setprio(0); } while (0)
; #define PG8_WAIT_V(n) asm volatile("s_waitcnt vmcnt(" #n ")" ::: "memory")
; #define PG8_WAIT_L(n) asm volatile("s_waitcnt lgkmcnt(" #n ")" ::: "memory")
; #define PG8_BAR __builtin_amdgcn_s_barrier()
; #define PG8_SCHED __builtin_amdgcn_sched_barrier(0)
; template <class Epi, class Sched, int NSEG, int KK, int LDA, int LDB>
; __device__ __forceinline__ void gemm_phase(LAS unsigned char* lds, const Gemm g, const Sched& S, const Epi& E) {
;     ...
;             PG8_LDA(At, 1, 1); PG8_STAGE(PG8_SB(1, 0), b3, voffB); PG8_STAGE(PG8_SB(1, 1), b3 + hstepB, voffB); PG8_STAGE(PG8_SA(1, 0), a3, voffA);
;             PG8_WAIT_V(8); PG8_WAIT_L(0); PG8_BAR; PG8_MMA(1, 0, At, B0); PG8_MMA(1, 1, At, B1); PG8_BAR; PG8_SCHED;
;         }
;         if (wr == 0) PG8_BAR;
	s_add_i32 s50, s63, s13
	v_lshl_add_u64 v[154:155], v[154:155], 0, s[28:29]
	s_mov_b32 m0, s50
	ds_read_b128 v[188:191], v157 offset:49152
	ds_read_b128 v[192:195], v157 offset:50176
	ds_read_b128 v[196:199], v157 offset:51200
	ds_read_b128 v[200:203], v157 offset:52224
	ds_read_b128 v[204:207], v157 offset:53248
	ds_read_b128 v[208:211], v157 offset:54272
	ds_read_b128 v[212:215], v157 offset:55296
	ds_read_b128 v[216:219], v157 offset:56320
	global_load_lds_dwordx4 v[154:155], off
	s_add_i32 m0, s50, 0x2000
	s_add_u32 s10, s10, 0x40080
	v_lshl_add_u64 v[154:155], v[166:167], 0, s[28:29]
	s_addc_u32 s11, s11, 0
	s_add_i32 s50, s77, s13
	global_load_lds_dwordx4 v[154:155], off
	v_lshl_add_u64 v[154:155], s[10:11], 0, v[146:147]
	s_mov_b32 m0, s50
	s_nop 0
	global_load_lds_dwordx4 v[154:155], off
	v_lshl_add_u64 v[154:155], s[10:11], 0, v[142:143]
	s_add_i32 m0, s50, 0x2000
	s_nop 0
	global_load_lds_dwordx4 v[154:155], off
	v_lshl_add_u64 v[154:155], v[220:221], 0, s[28:29]
	s_mov_b32 m0, s53
	s_nop 0
	global_load_lds_dwordx4 v[154:155], off
	v_lshl_add_u64 v[154:155], v[222:223], 0, s[28:29]
	s_mov_b32 m0, s54
	s_nop 0
	global_load_lds_dwordx4 v[154:155], off
	s_waitcnt vmcnt(8)
	s_waitcnt lgkmcnt(0)
	s_barrier
	s_setprio 1
	v_mfma_f32_16x16x32_bf16 v[62:65], v[130:133], v[188:191], v[62:65]
	v_mfma_f32_16x16x32_bf16 v[58:61], v[138:141], v[188:191], v[58:61]
	v_mfma_f32_16x16x32_bf16 v[46:49], v[130:133], v[196:199], v[46:49]
	v_mfma_f32_16x16x32_bf16 v[42:45], v[138:141], v[196:199], v[42:45]
	v_mfma_f32_16x16x32_bf16 v[30:33], v[130:133], v[204:207], v[30:33]
	v_mfma_f32_16x16x32_bf16 v[26:29], v[138:141], v[204:207], v[26:29]
	v_mfma_f32_16x16x32_bf16 v[14:17], v[130:133], v[212:215], v[14:17]
	v_mfma_f32_16x16x32_bf16 v[10:13], v[138:141], v[212:215], v[10:13]
	v_mfma_f32_16x16x32_bf16 v[62:65], v[134:137], v[192:195], v[62:65]
	v_mfma_f32_16x16x32_bf16 v[58:61], v[158:161], v[192:195], v[58:61]
	v_mfma_f32_16x16x32_bf16 v[46:49], v[134:137], v[200:203], v[46:49]
	v_mfma_f32_16x16x32_bf16 v[42:45], v[158:161], v[200:203], v[42:45]
	v_mfma_f32_16x16x32_bf16 v[30:33], v[134:137], v[208:211], v[30:33]
	v_mfma_f32_16x16x32_bf16 v[26:29], v[158:161], v[208:211], v[26:29]
	v_mfma_f32_16x16x32_bf16 v[14:17], v[134:137], v[216:219], v[14:17]
	v_mfma_f32_16x16x32_bf16 v[10:13], v[158:161], v[216:219], v[10:13]
	s_setprio 0
	s_setprio 1
	v_mfma_f32_16x16x32_bf16 v[54:57], v[162:165], v[188:191], v[54:57]
	v_mfma_f32_16x16x32_bf16 v[50:53], v[180:183], v[188:191], v[50:53]
	v_mfma_f32_16x16x32_bf16 v[38:41], v[162:165], v[196:199], v[38:41]
	v_mfma_f32_16x16x32_bf16 v[34:37], v[180:183], v[196:199], v[34:37]
	v_mfma_f32_16x16x32_bf16 v[22:25], v[162:165], v[204:207], v[22:25]
	v_mfma_f32_16x16x32_bf16 v[18:21], v[180:183], v[204:207], v[18:21]
	v_mfma_f32_16x16x32_bf16 v[6:9], v[162:165], v[212:215], v[6:9]
	v_mfma_f32_16x16x32_bf16 v[2:5], v[180:183], v[212:215], v[2:5]
	v_mfma_f32_16x16x32_bf16 v[54:57], v[176:179], v[192:195], v[54:57]
	v_mfma_f32_16x16x32_bf16 v[50:53], v[184:187], v[192:195], v[50:53]
	v_mfma_f32_16x16x32_bf16 v[38:41], v[176:179], v[200:203], v[38:41]
	v_mfma_f32_16x16x32_bf16 v[34:37], v[184:187], v[200:203], v[34:37]
	v_mfma_f32_16x16x32_bf16 v[22:25], v[176:179], v[208:211], v[22:25]
	v_mfma_f32_16x16x32_bf16 v[18:21], v[184:187], v[208:211], v[18:21]
	v_mfma_f32_16x16x32_bf16 v[6:9], v[176:179], v[216:219], v[6:9]
	v_mfma_f32_16x16x32_bf16 v[2:5], v[184:187], v[216:219], v[2:5]
	s_setprio 0
	s_barrier
	s_add_i32 s62, s62, 2
	s_add_u32 s40, s40, 0x100
	s_addc_u32 s41, s41, 0
	s_add_u32 s60, s60, 0x100
	s_addc_u32 s61, s61, 0
	s_cmp_gt_u32 s62, 13
	s_cbranch_scc0 .LBB0_388
	s_mov_b32 s101, 1
	s_and_b64 vcc, exec, s[24:25]
	s_cbranch_vccz .LBB0_391
	s_barrier

; #define PG8_STAGE(bufoff, gbase, voff) do { _Pragma("unroll") for (int _i = 0; _i < 2; ++_i) \
;         __builtin_amdgcn_global_load_lds((const unsigned*)((const char*)(gbase) + (voff)[_i]), (LAS unsigned*)(lds + (bufoff) + ldsw + _i * 8192), 16, 0, 0); } while (0)
; #define PG8_LDA(dst, b, h) do { _Pragma("unroll") for (int m = 0; m < 4; ++m) _Pragma("unroll") for (int k = 0; k < 2; ++k) dst[m][k] = *(const LAS bf16x8*)(lds + PG8_SA(b, h) + aoff + m * 2048 + k * 1024); } while (0)
; #define PG8_MMA(ai, bj, At, Bt) do { __builtin_amdgcn_s_setprio(1); _Pragma("unroll") for (int m = 0; m < 4; ++m) _Pragma("unroll") for (int n = 0; n < 2; ++n) _Pragma("unroll") for (int k = 0; k < 2; ++k) \
;         acc[ai][bj][m][n] = __builtin_amdgcn_mfma_f32_16x16x32_bf16(Bt[n][k], At[m][k], acc[ai][bj][m][n], 0, 0, 0); __builtin_amdgcn_s_setprio(0); } while (0)
; #define PG8_WAIT_V(n) asm volatile("s_waitcnt vmcnt(" #n ")" ::: "memory")
; #define PG8_WAIT_L(n) asm volatile("s_waitcnt lgkmcnt(" #n ")" ::: "memory")
; #define PG8_BAR __builtin_amdgcn_s_barrier()
; #define PG8_SCHED __builtin_amdgcn_sched_barrier(0)
; template <class Epi, class Sched, int NSEG, int KK, int LDA, int LDB>
; __device__ __forceinline__ void gemm_phase(LAS unsigned char* lds, const Gemm g, const Sched& S, const Epi& E) {
;     ...
;             PG8_WAIT_V(8); PG8_WAIT_L(0); PG8_BAR; PG8_MMA(0, 0, At, B0); PG8_MMA(0, 1, At, B1); PG8_BAR; PG8_SCHED;
;             PG8_LDA(At, 0, 1); PG8_STAGE(PG8_SB(0, 0), b2, voffB); PG8_STAGE(PG8_SB(0, 1), b2 + hstepB, voffB); PG8_STAGE(PG8_SA(0, 0), a2, voffA);
;             PG8_WAIT_V(8); PG8_WAIT_L(0); PG8_BAR; PG8_MMA(1, 0, At, B0); PG8_MMA(1, 1, At, B1); PG8_BAR; PG8_SCHED;
.Lskw_1_1:
	s_waitcnt lgkmcnt(0)
	s_barrier
	s_setprio 1
	v_mfma_f32_16x16x32_bf16 v[126:129], v[130:133], v[184:187], v[126:129]
	v_mfma_f32_16x16x32_bf16 v[122:125], v[138:141], v[184:187], v[122:125]
	v_mfma_f32_16x16x32_bf16 v[118:121], v[130:133], v[192:195], v[118:121]
	v_mfma_f32_16x16x32_bf16 v[114:117], v[138:141], v[192:195], v[114:117]
	v_mfma_f32_16x16x32_bf16 v[102:105], v[130:133], v[200:203], v[102:105]
	v_mfma_f32_16x16x32_bf16 v[98:101], v[138:141], v[200:203], v[98:101]
	v_mfma_f32_16x16x32_bf16 v[86:89], v[130:133], v[208:211], v[86:89]
	v_mfma_f32_16x16x32_bf16 v[82:85], v[138:141], v[208:211], v[82:85]
	v_mfma_f32_16x16x32_bf16 v[126:129], v[134:137], v[188:191], v[126:129]
	v_mfma_f32_16x16x32_bf16 v[122:125], v[156:159], v[188:191], v[122:125]
	v_mfma_f32_16x16x32_bf16 v[118:121], v[134:137], v[196:199], v[118:121]
	v_mfma_f32_16x16x32_bf16 v[114:117], v[156:159], v[196:199], v[114:117]
	v_mfma_f32_16x16x32_bf16 v[102:105], v[134:137], v[204:207], v[102:105]
	v_mfma_f32_16x16x32_bf16 v[98:101], v[156:159], v[204:207], v[98:101]
	v_mfma_f32_16x16x32_bf16 v[86:89], v[134:137], v[212:215], v[86:89]
	v_mfma_f32_16x16x32_bf16 v[82:85], v[156:159], v[212:215], v[82:85]
	s_setprio 0
	s_setprio 1
	v_mfma_f32_16x16x32_bf16 v[110:113], v[160:163], v[184:187], v[110:113]
	v_mfma_f32_16x16x32_bf16 v[106:109], v[176:179], v[184:187], v[106:109]
	v_mfma_f32_16x16x32_bf16 v[94:97], v[160:163], v[192:195], v[94:97]
	v_mfma_f32_16x16x32_bf16 v[90:93], v[176:179], v[192:195], v[90:93]
	v_mfma_f32_16x16x32_bf16 v[78:81], v[160:163], v[200:203], v[78:81]
	v_mfma_f32_16x16x32_bf16 v[74:77], v[176:179], v[200:203], v[74:77]
	v_mfma_f32_16x16x32_bf16 v[70:73], v[160:163], v[208:211], v[70:73]
	v_mfma_f32_16x16x32_bf16 v[66:69], v[176:179], v[208:211], v[66:69]
	v_mfma_f32_16x16x32_bf16 v[110:113], v[164:167], v[188:191], v[110:113]
	v_mfma_f32_16x16x32_bf16 v[106:109], v[180:183], v[188:191], v[106:109]
	v_mfma_f32_16x16x32_bf16 v[94:97], v[164:167], v[196:199], v[94:97]
	v_mfma_f32_16x16x32_bf16 v[90:93], v[180:183], v[196:199], v[90:93]
	v_mfma_f32_16x16x32_bf16 v[78:81], v[164:167], v[204:207], v[78:81]
	v_mfma_f32_16x16x32_bf16 v[74:77], v[180:183], v[204:207], v[74:77]
	v_mfma_f32_16x16x32_bf16 v[70:73], v[164:167], v[212:215], v[70:73]
	v_mfma_f32_16x16x32_bf16 v[66:69], v[180:183], v[212:215], v[66:69]
	s_setprio 0
	s_barrier
	s_add_i32 s63, s63, s23
	v_lshl_add_u64 v[216:217], s[10:11], 0, v[146:147]
	s_mov_b32 m0, s63
	ds_read_b128 v[184:187], v155 offset:16384
	ds_read_b128 v[188:191], v155 offset:17408
	ds_read_b128 v[192:195], v155 offset:18432
	ds_read_b128 v[196:199], v155 offset:19456
	ds_read_b128 v[200:203], v155 offset:20480
	ds_read_b128 v[204:207], v155 offset:21504
	ds_read_b128 v[208:211], v155 offset:22528
	ds_read_b128 v[212:215], v155 offset:23552
	global_load_lds_dwordx4 v[216:217], off
	s_add_i32 m0, s63, 0x2000
	s_add_u32 s94, s10, 0x40000
	v_lshl_add_u64 v[218:219], s[10:11], 0, v[142:143]
	s_addc_u32 s95, s11, 0
	s_add_i32 s63, s77, s23
	global_load_lds_dwordx4 v[218:219], off
	v_lshl_add_u64 v[220:221], s[94:95], 0, v[146:147]
	s_mov_b32 m0, s63
	v_lshl_add_u64 v[222:223], s[50:51], 0, v[144:145]
	global_load_lds_dwordx4 v[220:221], off
	v_lshl_add_u64 v[220:221], s[94:95], 0, v[142:143]
	s_add_i32 m0, s63, 0x2000
	s_nop 0
	global_load_lds_dwordx4 v[220:221], off
	v_lshl_add_u64 v[220:221], s[50:51], 0, v[148:149]
	s_mov_b32 m0, s26
	s_nop 0
	global_load_lds_dwordx4 v[220:221], off
	s_mov_b32 m0, s33
	s_nop 0
	global_load_lds_dwordx4 v[222:223], off
	s_cmp_lg_u32 s101, 0
	s_cbranch_scc1 .Lskw_1_2
	s_waitcnt vmcnt(8)
.Lskw_1_2:
	s_mov_b32 s101, 0
	s_waitcnt lgkmcnt(0)
	s_barrier
	s_setprio 1
	v_mfma_f32_16x16x32_bf16 v[62:65], v[130:133], v[184:187], v[62:65]
	v_mfma_f32_16x16x32_bf16 v[58:61], v[138:141], v[184:187], v[58:61]
	v_mfma_f32_16x16x32_bf16 v[54:57], v[130:133], v[192:195], v[54:57]
	v_mfma_f32_16x16x32_bf16 v[50:53], v[138:141], v[192:195], v[50:53]
	v_mfma_f32_16x16x32_bf16 v[38:41], v[130:133], v[200:203], v[38:41]
	v_mfma_f32_16x16x32_bf16 v[34:37], v[138:141], v[200:203], v[34:37]
	v_mfma_f32_16x16x32_bf16 v[22:25], v[130:133], v[208:211], v[22:25]
	v_mfma_f32_16x16x32_bf16 v[18:21], v[138:141], v[208:211], v[18:21]
	v_mfma_f32_16x16x32_bf16 v[62:65], v[134:137], v[188:191], v[62:65]
	v_mfma_f32_16x16x32_bf16 v[58:61], v[156:159], v[188:191], v[58:61]
	v_mfma_f32_16x16x32_bf16 v[54:57], v[134:137], v[196:199], v[54:57]
	v_mfma_f32_16x16x32_bf16 v[50:53], v[156:159], v[196:199], v[50:53]
	v_mfma_f32_16x16x32_bf16 v[38:41], v[134:137], v[204:207], v[38:41]
	v_mfma_f32_16x16x32_bf16 v[34:37], v[156:159], v[204:207], v[34:37]
	v_mfma_f32_16x16x32_bf16 v[22:25], v[134:137], v[212:215], v[22:25]
	v_mfma_f32_16x16x32_bf16 v[18:21], v[156:159], v[212:215], v[18:21]
	s_setprio 0
	s_setprio 1
	v_mfma_f32_16x16x32_bf16 v[46:49], v[160:163], v[184:187], v[46:49]
	v_mfma_f32_16x16x32_bf16 v[42:45], v[176:179], v[184:187], v[42:45]
	v_mfma_f32_16x16x32_bf16 v[30:33], v[160:163], v[192:195], v[30:33]
	v_mfma_f32_16x16x32_bf16 v[26:29], v[176:179], v[192:195], v[26:29]
	v_mfma_f32_16x16x32_bf16 v[14:17], v[160:163], v[200:203], v[14:17]
	v_mfma_f32_16x16x32_bf16 v[10:13], v[176:179], v[200:203], v[10:13]
	v_mfma_f32_16x16x32_bf16 v[6:9], v[160:163], v[208:211], v[6:9]
	v_mfma_f32_16x16x32_bf16 v[2:5], v[176:179], v[208:211], v[2:5]
	v_mfma_f32_16x16x32_bf16 v[46:49], v[164:167], v[188:191], v[46:49]
	v_mfma_f32_16x16x32_bf16 v[42:45], v[180:183], v[188:191], v[42:45]
	v_mfma_f32_16x16x32_bf16 v[30:33], v[164:167], v[196:199], v[30:33]
	v_mfma_f32_16x16x32_bf16 v[26:29], v[180:183], v[196:199], v[26:29]
	v_mfma_f32_16x16x32_bf16 v[14:17], v[164:167], v[204:207], v[14:17]
	v_mfma_f32_16x16x32_bf16 v[10:13], v[180:183], v[204:207], v[10:13]
	v_mfma_f32_16x16x32_bf16 v[6:9], v[164:167], v[212:215], v[6:9]
	v_mfma_f32_16x16x32_bf16 v[2:5], v[180:183], v[212:215], v[2:5]
	s_setprio 0
	s_barrier
; #define PG8_STAGE(bufoff, gbase, voff) do { _Pragma("unroll") for (int _i = 0; _i < 2; ++_i) \
;         __builtin_amdgcn_global_load_lds((const unsigned*)((const char*)(gbase) + (voff)[_i]), (LAS unsigned*)(lds + (bufoff) + ldsw + _i * 8192), 16, 0, 0); } while (0)
; #define PG8_LDA(dst, b, h) do { _Pragma("unroll") for (int m = 0; m < 4; ++m) _Pragma("unroll") for (int k = 0; k < 2; ++k) dst[m][k] = *(const LAS bf16x8*)(lds + PG8_SA(b, h) + aoff + m * 2048 + k * 1024); } while (0)
; #define PG8_LDB(dst, b, h) do { _Pragma("unroll") for (int n = 0; n < 2; ++n) _Pragma("unroll") for (int k = 0; k < 2; ++k) dst[n][k] = *(const LAS bf16x8*)(lds + PG8_SB(b, h) + boff + n * 2048 + k * 1024); } while (0)
; #define PG8_MMA(ai, bj, At, Bt) do { __builtin_amdgcn_s_setprio(1); _Pragma("unroll") for (int m = 0; m < 4; ++m) _Pragma("unroll") for (int n = 0; n < 2; ++n) _Pragma("unroll") for (int k = 0; k < 2; ++k) \
;         acc[ai][bj][m][n] = __builtin_amdgcn_mfma_f32_16x16x32_bf16(Bt[n][k], At[m][k], acc[ai][bj][m][n], 0, 0, 0); __builtin_amdgcn_s_setprio(0); } while (0)
; #define PG8_WAIT_V(n) asm volatile("s_waitcnt vmcnt(" #n ")" ::: "memory")
; #define PG8_WAIT_L(n) asm volatile("s_waitcnt lgkmcnt(" #n ")" ::: "memory")
; #define PG8_BAR __builtin_amdgcn_s_barrier()
; #define PG8_SCHED __builtin_amdgcn_sched_barrier(0)
; template <class Epi, class Sched, int NSEG, int KK, int LDA, int LDB>
; __device__ __forceinline__ void gemm_phase(LAS unsigned char* lds, const Gemm g, const Sched& S, const Epi& E) {
;     ...
;             PG8_LDB(B0, 1, 0); PG8_LDB(B1, 1, 1); PG8_SCHED; PG8_LDA(At, 1, 0); PG8_STAGE(PG8_SA(0, 1), a2 + hstepA, voffA);
;             PG8_WAIT_V(8); PG8_WAIT_L(0); PG8_BAR; PG8_MMA(0, 0, At, B0); PG8_MMA(0, 1, At, B1); PG8_BAR; PG8_SCHED;
	s_add_i32 s63, 0, 0x18000
	v_add_u32_e32 v0, s63, v154
	s_add_i32 s77, 0, 0x1c000
	ds_read_b128 v[130:133], v0
	ds_read_b128 v[134:137], v0 offset:1024
	ds_read_b128 v[138:141], v0 offset:2048
	ds_read_b128 v[156:159], v0 offset:3072
	v_add_u32_e32 v0, s77, v154
	ds_read_b128 v[160:163], v0
	ds_read_b128 v[164:167], v0 offset:1024
	ds_read_b128 v[176:179], v0 offset:2048
	ds_read_b128 v[180:183], v0 offset:3072
	s_add_u32 s50, s50, 0x40000
	s_addc_u32 s51, s51, 0
	s_mov_b32 m0, s38
	v_lshl_add_u64 v[224:225], s[50:51], 0, v[148:149]
	ds_read_b128 v[184:187], v155 offset:32768
	ds_read_b128 v[188:191], v155 offset:33792
	ds_read_b128 v[192:195], v155 offset:34816
	ds_read_b128 v[196:199], v155 offset:35840
	ds_read_b128 v[200:203], v155 offset:36864
	ds_read_b128 v[204:207], v155 offset:37888
	ds_read_b128 v[208:211], v155 offset:38912
	ds_read_b128 v[212:215], v155 offset:39936
	global_load_lds_dwordx4 v[224:225], off
	v_lshl_add_u64 v[224:225], s[50:51], 0, v[144:145]
	s_mov_b32 m0, s39
	s_nop 0
	global_load_lds_dwordx4 v[224:225], off
	s_waitcnt vmcnt(8)
	s_waitcnt lgkmcnt(0)
	s_barrier
	s_setprio 1
	v_mfma_f32_16x16x32_bf16 v[126:129], v[130:133], v[184:187], v[126:129]
	v_mfma_f32_16x16x32_bf16 v[122:125], v[138:141], v[184:187], v[122:125]
	v_mfma_f32_16x16x32_bf16 v[118:121], v[130:133], v[192:195], v[118:121]
	v_mfma_f32_16x16x32_bf16 v[114:117], v[138:141], v[192:195], v[114:117]
	v_mfma_f32_16x16x32_bf16 v[102:105], v[130:133], v[200:203], v[102:105]
	v_mfma_f32_16x16x32_bf16 v[98:101], v[138:141], v[200:203], v[98:101]
	v_mfma_f32_16x16x32_bf16 v[86:89], v[130:133], v[208:211], v[86:89]
	v_mfma_f32_16x16x32_bf16 v[82:85], v[138:141], v[208:211], v[82:85]
	v_mfma_f32_16x16x32_bf16 v[126:129], v[134:137], v[188:191], v[126:129]
	v_mfma_f32_16x16x32_bf16 v[122:125], v[156:159], v[188:191], v[122:125]
	v_mfma_f32_16x16x32_bf16 v[118:121], v[134:137], v[196:199], v[118:121]
	v_mfma_f32_16x16x32_bf16 v[114:117], v[156:159], v[196:199], v[114:117]
	v_mfma_f32_16x16x32_bf16 v[102:105], v[134:137], v[204:207], v[102:105]
	v_mfma_f32_16x16x32_bf16 v[98:101], v[156:159], v[204:207], v[98:101]
	v_mfma_f32_16x16x32_bf16 v[86:89], v[134:137], v[212:215], v[86:89]
	v_mfma_f32_16x16x32_bf16 v[82:85], v[156:159], v[212:215], v[82:85]
	s_setprio 0
	s_setprio 1
	v_mfma_f32_16x16x32_bf16 v[110:113], v[160:163], v[184:187], v[110:113]
	v_mfma_f32_16x16x32_bf16 v[106:109], v[176:179], v[184:187], v[106:109]
	v_mfma_f32_16x16x32_bf16 v[94:97], v[160:163], v[192:195], v[94:97]
	v_mfma_f32_16x16x32_bf16 v[90:93], v[176:179], v[192:195], v[90:93]
	v_mfma_f32_16x16x32_bf16 v[78:81], v[160:163], v[200:203], v[78:81]
	v_mfma_f32_16x16x32_bf16 v[74:77], v[176:179], v[200:203], v[74:77]
	v_mfma_f32_16x16x32_bf16 v[70:73], v[160:163], v[208:211], v[70:73]
	v_mfma_f32_16x16x32_bf16 v[66:69], v[176:179], v[208:211], v[66:69]
	v_mfma_f32_16x16x32_bf16 v[110:113], v[164:167], v[188:191], v[110:113]
	v_mfma_f32_16x16x32_bf16 v[106:109], v[180:183], v[188:191], v[106:109]
	v_mfma_f32_16x16x32_bf16 v[94:97], v[164:167], v[196:199], v[94:97]
	v_mfma_f32_16x16x32_bf16 v[90:93], v[180:183], v[196:199], v[90:93]
	v_mfma_f32_16x16x32_bf16 v[78:81], v[164:167], v[204:207], v[78:81]
	v_mfma_f32_16x16x32_bf16 v[74:77], v[180:183], v[204:207], v[74:77]
	v_mfma_f32_16x16x32_bf16 v[70:73], v[164:167], v[212:215], v[70:73]
	v_mfma_f32_16x16x32_bf16 v[66:69], v[180:183], v[212:215], v[66:69]
	s_setprio 0
	s_barrier
; #define PG8_STAGE(bufoff, gbase, voff) do { _Pragma("unroll") for (int _i = 0; _i < 2; ++_i) \
;         __builtin_amdgcn_global_load_lds((const unsigned*)((const char*)(gbase) + (voff)[_i]), (LAS unsigned*)(lds + (bufoff) + ldsw + _i * 8192), 16, 0, 0); } while (0)
; #define PG8_LDA(dst, b, h) do { _Pragma("unroll") for (int m = 0; m < 4; ++m) _Pragma("unroll") for (int k = 0; k < 2; ++k) dst[m][k] = *(const LAS bf16x8*)(lds + PG8_SA(b, h) + aoff + m * 2048 + k * 1024); } while (0)
; #define PG8_MMA(ai, bj, At, Bt) do { __builtin_amdgcn_s_setprio(1); _Pragma("unroll") for (int m = 0; m < 4; ++m) _Pragma("unroll") for (int n = 0; n < 2; ++n) _Pragma("unroll") for (int k = 0; k < 2; ++k) \
;         acc[ai][bj][m][n] = __builtin_amdgcn_mfma_f32_16x16x32_bf16(Bt[n][k], At[m][k], acc[ai][bj][m][n], 0, 0, 0); __builtin_amdgcn_s_setprio(0); } while (0)
; #define PG8_WAIT_V(n) asm volatile("s_waitcnt vmcnt(" #n ")" ::: "memory")
; #define PG8_WAIT_L(n) asm volatile("s_waitcnt lgkmcnt(" #n ")" ::: "memory")
; #define PG8_BAR __builtin_amdgcn_s_barrier()
; #define PG8_SCHED __builtin_amdgcn_sched_barrier(0)
; template <class Epi, class Sched, int NSEG, int KK, int LDA, int LDB>
; __device__ __forceinline__ void gemm_phase(LAS unsigned char* lds, const Gemm g, const Sched& S, const Epi& E) {
;     ...
;             PG8_LDA(At, 1, 1); PG8_STAGE(PG8_SB(1, 0), b3, voffB); PG8_STAGE(PG8_SB(1, 1), b3 + hstepB, voffB); PG8_STAGE(PG8_SA(1, 0), a3, voffA);
;             PG8_WAIT_V(8); PG8_WAIT_L(0); PG8_BAR; PG8_MMA(1, 0, At, B0); PG8_MMA(1, 1, At, B1); PG8_BAR; PG8_SCHED;
;         }
;         if (wr == 0) PG8_BAR;
	s_add_i32 s50, s63, s23
	v_lshl_add_u64 v[216:217], v[216:217], 0, s[28:29]
	s_mov_b32 m0, s50
	ds_read_b128 v[184:187], v155 offset:49152
	ds_read_b128 v[188:191], v155 offset:50176
	ds_read_b128 v[192:195], v155 offset:51200
	ds_read_b128 v[196:199], v155 offset:52224
	ds_read_b128 v[200:203], v155 offset:53248
	ds_read_b128 v[204:207], v155 offset:54272
	ds_read_b128 v[208:211], v155 offset:55296
	ds_read_b128 v[212:215], v155 offset:56320
	global_load_lds_dwordx4 v[216:217], off
	s_add_i32 m0, s50, 0x2000
	s_add_u32 s10, s10, 0x40080
	v_lshl_add_u64 v[216:217], v[218:219], 0, s[28:29]
	s_addc_u32 s11, s11, 0
	s_add_i32 s50, s77, s23
	global_load_lds_dwordx4 v[216:217], off
	v_lshl_add_u64 v[216:217], s[10:11], 0, v[146:147]
	s_mov_b32 m0, s50
	s_nop 0
	global_load_lds_dwordx4 v[216:217], off
	v_lshl_add_u64 v[216:217], s[10:11], 0, v[142:143]
	s_add_i32 m0, s50, 0x2000
	s_nop 0
	global_load_lds_dwordx4 v[216:217], off
	v_lshl_add_u64 v[216:217], v[220:221], 0, s[28:29]
	s_mov_b32 m0, s53
	s_nop 0
	global_load_lds_dwordx4 v[216:217], off
	v_lshl_add_u64 v[216:217], v[222:223], 0, s[28:29]
	s_mov_b32 m0, s54
	s_nop 0
	global_load_lds_dwordx4 v[216:217], off
	s_waitcnt vmcnt(8)
	s_waitcnt lgkmcnt(0)
	s_barrier
	s_setprio 1
	v_mfma_f32_16x16x32_bf16 v[62:65], v[130:133], v[184:187], v[62:65]
	v_mfma_f32_16x16x32_bf16 v[58:61], v[138:141], v[184:187], v[58:61]
	v_mfma_f32_16x16x32_bf16 v[54:57], v[130:133], v[192:195], v[54:57]
	v_mfma_f32_16x16x32_bf16 v[50:53], v[138:141], v[192:195], v[50:53]
	v_mfma_f32_16x16x32_bf16 v[38:41], v[130:133], v[200:203], v[38:41]
	v_mfma_f32_16x16x32_bf16 v[34:37], v[138:141], v[200:203], v[34:37]
	v_mfma_f32_16x16x32_bf16 v[22:25], v[130:133], v[208:211], v[22:25]
	v_mfma_f32_16x16x32_bf16 v[18:21], v[138:141], v[208:211], v[18:21]
	v_mfma_f32_16x16x32_bf16 v[62:65], v[134:137], v[188:191], v[62:65]
	v_mfma_f32_16x16x32_bf16 v[58:61], v[156:159], v[188:191], v[58:61]
	v_mfma_f32_16x16x32_bf16 v[54:57], v[134:137], v[196:199], v[54:57]
	v_mfma_f32_16x16x32_bf16 v[50:53], v[156:159], v[196:199], v[50:53]
	v_mfma_f32_16x16x32_bf16 v[38:41], v[134:137], v[204:207], v[38:41]
	v_mfma_f32_16x16x32_bf16 v[34:37], v[156:159], v[204:207], v[34:37]
	v_mfma_f32_16x16x32_bf16 v[22:25], v[134:137], v[212:215], v[22:25]
	v_mfma_f32_16x16x32_bf16 v[18:21], v[156:159], v[212:215], v[18:21]
	s_setprio 0
	s_setprio 1
	v_mfma_f32_16x16x32_bf16 v[46:49], v[160:163], v[184:187], v[46:49]
	v_mfma_f32_16x16x32_bf16 v[42:45], v[176:179], v[184:187], v[42:45]
	v_mfma_f32_16x16x32_bf16 v[30:33], v[160:163], v[192:195], v[30:33]
	v_mfma_f32_16x16x32_bf16 v[26:29], v[176:179], v[192:195], v[26:29]
	v_mfma_f32_16x16x32_bf16 v[14:17], v[160:163], v[200:203], v[14:17]
	v_mfma_f32_16x16x32_bf16 v[10:13], v[176:179], v[200:203], v[10:13]
	v_mfma_f32_16x16x32_bf16 v[6:9], v[160:163], v[208:211], v[6:9]
	v_mfma_f32_16x16x32_bf16 v[2:5], v[176:179], v[208:211], v[2:5]
	v_mfma_f32_16x16x32_bf16 v[46:49], v[164:167], v[188:191], v[46:49]
	v_mfma_f32_16x16x32_bf16 v[42:45], v[180:183], v[188:191], v[42:45]
	v_mfma_f32_16x16x32_bf16 v[30:33], v[164:167], v[196:199], v[30:33]
	v_mfma_f32_16x16x32_bf16 v[26:29], v[180:183], v[196:199], v[26:29]
	v_mfma_f32_16x16x32_bf16 v[14:17], v[164:167], v[204:207], v[14:17]
	v_mfma_f32_16x16x32_bf16 v[10:13], v[180:183], v[204:207], v[10:13]
	v_mfma_f32_16x16x32_bf16 v[6:9], v[164:167], v[212:215], v[6:9]
	v_mfma_f32_16x16x32_bf16 v[2:5], v[180:183], v[212:215], v[2:5]
	s_setprio 0
	s_barrier
	s_add_i32 s62, s62, 2
	s_add_u32 s48, s48, 0x100
	s_addc_u32 s49, s49, 0
	s_add_u32 s60, s60, 0x100
	s_addc_u32 s61, s61, 0
	s_cmp_gt_u32 s62, 13
	s_cbranch_scc0 .LBB0_677
	s_mov_b32 s101, 1
	s_and_b64 vcc, exec, s[8:9]
	s_cbranch_vccz .LBB0_680
	s_barrier

; #define PG8_STAGE(bufoff, gbase, voff) do { _Pragma("unroll") for (int _i = 0; _i < 2; ++_i) \
;         __builtin_amdgcn_global_load_lds((const unsigned*)((const char*)(gbase) + (voff)[_i]), (LAS unsigned*)(lds + (bufoff) + ldsw + _i * 8192), 16, 0, 0); } while (0)
; #define PG8_LDA(dst, b, h) do { _Pragma("unroll") for (int m = 0; m < 4; ++m) _Pragma("unroll") for (int k = 0; k < 2; ++k) dst[m][k] = *(const LAS bf16x8*)(lds + PG8_SA(b, h) + aoff + m * 2048 + k * 1024); } while (0)
; #define PG8_MMA(ai, bj, At, Bt) do { __builtin_amdgcn_s_setprio(1); _Pragma("unroll") for (int m = 0; m < 4; ++m) _Pragma("unroll") for (int n = 0; n < 2; ++n) _Pragma("unroll") for (int k = 0; k < 2; ++k) \
;         acc[ai][bj][m][n] = __builtin_amdgcn_mfma_f32_16x16x32_bf16(Bt[n][k], At[m][k], acc[ai][bj][m][n], 0, 0, 0); __builtin_amdgcn_s_setprio(0); } while (0)
; #define PG8_WAIT_V(n) asm volatile("s_waitcnt vmcnt(" #n ")" ::: "memory")
; #define PG8_WAIT_L(n) asm volatile("s_waitcnt lgkmcnt(" #n ")" ::: "memory")
; #define PG8_BAR __builtin_amdgcn_s_barrier()
; #define PG8_SCHED __builtin_amdgcn_sched_barrier(0)
; template <class Epi, class Sched, int NSEG, int KK, int LDA, int LDB>
; __device__ __forceinline__ void gemm_phase(LAS unsigned char* lds, const Gemm g, const Sched& S, const Epi& E) {
;     ...
;             PG8_WAIT_V(8); PG8_WAIT_L(0); PG8_BAR; PG8_MMA(0, 0, At, B0); PG8_MMA(0, 1, At, B1); PG8_BAR; PG8_SCHED;
;             PG8_LDA(At, 0, 1); PG8_STAGE(PG8_SB(0, 0), b2, voffB); PG8_STAGE(PG8_SB(0, 1), b2 + hstepB, voffB); PG8_STAGE(PG8_SA(0, 0), a2, voffA);
;             PG8_WAIT_V(8); PG8_WAIT_L(0); PG8_BAR; PG8_MMA(1, 0, At, B0); PG8_MMA(1, 1, At, B1); PG8_BAR; PG8_SCHED;
.Lskw_2_1:
	s_waitcnt lgkmcnt(0)
	s_barrier
	s_setprio 1
	v_mfma_f32_16x16x32_bf16 v[126:129], v[140:143], v[180:183], v[126:129]
	v_mfma_f32_16x16x32_bf16 v[122:125], v[148:151], v[180:183], v[122:125]
	v_mfma_f32_16x16x32_bf16 v[118:121], v[140:143], v[188:191], v[118:121]
	v_mfma_f32_16x16x32_bf16 v[114:117], v[148:151], v[188:191], v[114:117]
	v_mfma_f32_16x16x32_bf16 v[110:113], v[140:143], v[196:199], v[110:113]
	v_mfma_f32_16x16x32_bf16 v[106:109], v[148:151], v[196:199], v[106:109]
	v_mfma_f32_16x16x32_bf16 v[102:105], v[140:143], v[204:207], v[102:105]
	v_mfma_f32_16x16x32_bf16 v[98:101], v[148:151], v[204:207], v[98:101]
	v_mfma_f32_16x16x32_bf16 v[126:129], v[144:147], v[184:187], v[126:129]
	v_mfma_f32_16x16x32_bf16 v[122:125], v[152:155], v[184:187], v[122:125]
	v_mfma_f32_16x16x32_bf16 v[118:121], v[144:147], v[192:195], v[118:121]
	v_mfma_f32_16x16x32_bf16 v[114:117], v[152:155], v[192:195], v[114:117]
	v_mfma_f32_16x16x32_bf16 v[110:113], v[144:147], v[200:203], v[110:113]
	v_mfma_f32_16x16x32_bf16 v[106:109], v[152:155], v[200:203], v[106:109]
	v_mfma_f32_16x16x32_bf16 v[102:105], v[144:147], v[208:211], v[102:105]
	v_mfma_f32_16x16x32_bf16 v[98:101], v[152:155], v[208:211], v[98:101]
	s_setprio 0
	s_setprio 1
	v_mfma_f32_16x16x32_bf16 v[94:97], v[156:159], v[180:183], v[94:97]
	v_mfma_f32_16x16x32_bf16 v[90:93], v[164:167], v[180:183], v[90:93]
	v_mfma_f32_16x16x32_bf16 v[86:89], v[156:159], v[188:191], v[86:89]
	v_mfma_f32_16x16x32_bf16 v[82:85], v[164:167], v[188:191], v[82:85]
	v_mfma_f32_16x16x32_bf16 v[78:81], v[156:159], v[196:199], v[78:81]
	v_mfma_f32_16x16x32_bf16 v[74:77], v[164:167], v[196:199], v[74:77]
	v_mfma_f32_16x16x32_bf16 v[70:73], v[156:159], v[204:207], v[70:73]
	v_mfma_f32_16x16x32_bf16 v[66:69], v[164:167], v[204:207], v[66:69]
	v_mfma_f32_16x16x32_bf16 v[94:97], v[160:163], v[184:187], v[94:97]
	v_mfma_f32_16x16x32_bf16 v[90:93], v[176:179], v[184:187], v[90:93]
	v_mfma_f32_16x16x32_bf16 v[86:89], v[160:163], v[192:195], v[86:89]
	v_mfma_f32_16x16x32_bf16 v[82:85], v[176:179], v[192:195], v[82:85]
	v_mfma_f32_16x16x32_bf16 v[78:81], v[160:163], v[200:203], v[78:81]
	v_mfma_f32_16x16x32_bf16 v[74:77], v[176:179], v[200:203], v[74:77]
	v_mfma_f32_16x16x32_bf16 v[70:73], v[160:163], v[208:211], v[70:73]
	v_mfma_f32_16x16x32_bf16 v[66:69], v[176:179], v[208:211], v[66:69]
	s_setprio 0
	s_barrier
	s_add_i32 s8, s83, s53
	v_lshl_add_u64 v[212:213], s[10:11], 0, v[0:1]
	s_mov_b32 m0, s8
	ds_read_b128 v[180:183], v245 offset:16384
	ds_read_b128 v[184:187], v245 offset:17408
	ds_read_b128 v[188:191], v245 offset:18432
	ds_read_b128 v[192:195], v245 offset:19456
	ds_read_b128 v[196:199], v245 offset:20480
	ds_read_b128 v[200:203], v245 offset:21504
	ds_read_b128 v[204:207], v245 offset:22528
	ds_read_b128 v[208:211], v245 offset:23552
	global_load_lds_dwordx4 v[212:213], off
	s_add_i32 m0, s8, 0x2000
	s_add_u32 s8, s10, 0x20000
	v_lshl_add_u64 v[214:215], s[10:11], 0, v[130:131]
	s_addc_u32 s9, s11, 0
	s_add_i32 s83, s91, s53
	global_load_lds_dwordx4 v[214:215], off
	v_lshl_add_u64 v[216:217], s[8:9], 0, v[0:1]
	s_mov_b32 m0, s83
	v_lshl_add_u64 v[218:219], s[44:45], 0, v[132:133]
	global_load_lds_dwordx4 v[216:217], off
	v_lshl_add_u64 v[216:217], s[8:9], 0, v[130:131]
	s_add_i32 m0, s83, 0x2000
	s_nop 0
	global_load_lds_dwordx4 v[216:217], off
	v_lshl_add_u64 v[216:217], s[44:45], 0, v[134:135]
	s_mov_b32 m0, s54
	s_nop 0
	global_load_lds_dwordx4 v[216:217], off
	s_mov_b32 m0, s55
	s_nop 0
	global_load_lds_dwordx4 v[218:219], off
	s_cmp_lg_u32 s101, 0
	s_cbranch_scc1 .Lskw_2_2
	s_waitcnt vmcnt(8)
.Lskw_2_2:
	s_mov_b32 s101, 0
	s_waitcnt lgkmcnt(0)
	s_barrier
	s_setprio 1
	v_mfma_f32_16x16x32_bf16 v[62:65], v[140:143], v[180:183], v[62:65]
	v_mfma_f32_16x16x32_bf16 v[58:61], v[148:151], v[180:183], v[58:61]
	v_mfma_f32_16x16x32_bf16 v[54:57], v[140:143], v[188:191], v[54:57]
	v_mfma_f32_16x16x32_bf16 v[50:53], v[148:151], v[188:191], v[50:53]
	v_mfma_f32_16x16x32_bf16 v[46:49], v[140:143], v[196:199], v[46:49]
	v_mfma_f32_16x16x32_bf16 v[42:45], v[148:151], v[196:199], v[42:45]
	v_mfma_f32_16x16x32_bf16 v[38:41], v[140:143], v[204:207], v[38:41]
	v_mfma_f32_16x16x32_bf16 v[34:37], v[148:151], v[204:207], v[34:37]
	v_mfma_f32_16x16x32_bf16 v[62:65], v[144:147], v[184:187], v[62:65]
	v_mfma_f32_16x16x32_bf16 v[58:61], v[152:155], v[184:187], v[58:61]
	v_mfma_f32_16x16x32_bf16 v[54:57], v[144:147], v[192:195], v[54:57]
	v_mfma_f32_16x16x32_bf16 v[50:53], v[152:155], v[192:195], v[50:53]
	v_mfma_f32_16x16x32_bf16 v[46:49], v[144:147], v[200:203], v[46:49]
	v_mfma_f32_16x16x32_bf16 v[42:45], v[152:155], v[200:203], v[42:45]
	v_mfma_f32_16x16x32_bf16 v[38:41], v[144:147], v[208:211], v[38:41]
	v_mfma_f32_16x16x32_bf16 v[34:37], v[152:155], v[208:211], v[34:37]
	s_setprio 0
	s_setprio 1
	v_mfma_f32_16x16x32_bf16 v[30:33], v[156:159], v[180:183], v[30:33]
	v_mfma_f32_16x16x32_bf16 v[26:29], v[164:167], v[180:183], v[26:29]
	v_mfma_f32_16x16x32_bf16 v[22:25], v[156:159], v[188:191], v[22:25]
	v_mfma_f32_16x16x32_bf16 v[18:21], v[164:167], v[188:191], v[18:21]
	v_mfma_f32_16x16x32_bf16 v[14:17], v[156:159], v[196:199], v[14:17]
	v_mfma_f32_16x16x32_bf16 v[10:13], v[164:167], v[196:199], v[10:13]
	v_mfma_f32_16x16x32_bf16 v[6:9], v[156:159], v[204:207], v[6:9]
	v_mfma_f32_16x16x32_bf16 v[2:5], v[164:167], v[204:207], v[2:5]
	v_mfma_f32_16x16x32_bf16 v[30:33], v[160:163], v[184:187], v[30:33]
	v_mfma_f32_16x16x32_bf16 v[26:29], v[176:179], v[184:187], v[26:29]
	v_mfma_f32_16x16x32_bf16 v[22:25], v[160:163], v[192:195], v[22:25]
	v_mfma_f32_16x16x32_bf16 v[18:21], v[176:179], v[192:195], v[18:21]
	v_mfma_f32_16x16x32_bf16 v[14:17], v[160:163], v[200:203], v[14:17]
	v_mfma_f32_16x16x32_bf16 v[10:13], v[176:179], v[200:203], v[10:13]
	v_mfma_f32_16x16x32_bf16 v[6:9], v[160:163], v[208:211], v[6:9]
	v_mfma_f32_16x16x32_bf16 v[2:5], v[176:179], v[208:211], v[2:5]
	s_setprio 0
	s_barrier
; #define PG8_STAGE(bufoff, gbase, voff) do { _Pragma("unroll") for (int _i = 0; _i < 2; ++_i) \
;         __builtin_amdgcn_global_load_lds((const unsigned*)((const char*)(gbase) + (voff)[_i]), (LAS unsigned*)(lds + (bufoff) + ldsw + _i * 8192), 16, 0, 0); } while (0)
; #define PG8_LDA(dst, b, h) do { _Pragma("unroll") for (int m = 0; m < 4; ++m) _Pragma("unroll") for (int k = 0; k < 2; ++k) dst[m][k] = *(const LAS bf16x8*)(lds + PG8_SA(b, h) + aoff + m * 2048 + k * 1024); } while (0)
; #define PG8_LDB(dst, b, h) do { _Pragma("unroll") for (int n = 0; n < 2; ++n) _Pragma("unroll") for (int k = 0; k < 2; ++k) dst[n][k] = *(const LAS bf16x8*)(lds + PG8_SB(b, h) + boff + n * 2048 + k * 1024); } while (0)
; #define PG8_MMA(ai, bj, At, Bt) do { __builtin_amdgcn_s_setprio(1); _Pragma("unroll") for (int m = 0; m < 4; ++m) _Pragma("unroll") for (int n = 0; n < 2; ++n) _Pragma("unroll") for (int k = 0; k < 2; ++k) \
;         acc[ai][bj][m][n] = __builtin_amdgcn_mfma_f32_16x16x32_bf16(Bt[n][k], At[m][k], acc[ai][bj][m][n], 0, 0, 0); __builtin_amdgcn_s_setprio(0); } while (0)
; #define PG8_WAIT_V(n) asm volatile("s_waitcnt vmcnt(" #n ")" ::: "memory")
; #define PG8_WAIT_L(n) asm volatile("s_waitcnt lgkmcnt(" #n ")" ::: "memory")
; #define PG8_BAR __builtin_amdgcn_s_barrier()
; #define PG8_SCHED __builtin_amdgcn_sched_barrier(0)
; template <class Epi, class Sched, int NSEG, int KK, int LDA, int LDB>
; __device__ __forceinline__ void gemm_phase(LAS unsigned char* lds, const Gemm g, const Sched& S, const Epi& E) {
;     ...
;             PG8_LDB(B0, 1, 0); PG8_LDB(B1, 1, 1); PG8_SCHED; PG8_LDA(At, 1, 0); PG8_STAGE(PG8_SA(0, 1), a2 + hstepA, voffA);
;             PG8_WAIT_V(8); PG8_WAIT_L(0); PG8_BAR; PG8_MMA(0, 0, At, B0); PG8_MMA(0, 1, At, B1); PG8_BAR; PG8_SCHED;
	s_add_i32 s83, 0, 0x18000
	s_add_i32 s91, 0, 0x1c000
	v_add_u32_e32 v152, s83, v244
	v_add_u32_e32 v172, s91, v244
	ds_read_b128 v[140:143], v152
	ds_read_b128 v[144:147], v152 offset:1024
	ds_read_b128 v[148:151], v152 offset:2048
	ds_read_b128 v[152:155], v152 offset:3072
	ds_read_b128 v[156:159], v172
	ds_read_b128 v[160:163], v172 offset:1024
	ds_read_b128 v[164:167], v172 offset:2048
	ds_read_b128 v[176:179], v172 offset:3072
	s_add_u32 s8, s44, 0x120000
	s_addc_u32 s9, s45, 0
	s_mov_b32 m0, s56
	v_lshl_add_u64 v[220:221], s[8:9], 0, v[134:135]
	ds_read_b128 v[180:183], v245 offset:32768
	ds_read_b128 v[184:187], v245 offset:33792
	ds_read_b128 v[188:191], v245 offset:34816
	ds_read_b128 v[192:195], v245 offset:35840
	ds_read_b128 v[196:199], v245 offset:36864
	ds_read_b128 v[200:203], v245 offset:37888
	ds_read_b128 v[204:207], v245 offset:38912
	ds_read_b128 v[208:211], v245 offset:39936
	global_load_lds_dwordx4 v[220:221], off
	v_lshl_add_u64 v[220:221], s[8:9], 0, v[132:133]
	s_mov_b32 m0, s57
	s_nop 0
	global_load_lds_dwordx4 v[220:221], off
	s_waitcnt vmcnt(8)
	s_waitcnt lgkmcnt(0)
	s_barrier
	s_setprio 1
	v_mfma_f32_16x16x32_bf16 v[126:129], v[140:143], v[180:183], v[126:129]
	v_mfma_f32_16x16x32_bf16 v[122:125], v[148:151], v[180:183], v[122:125]
	v_mfma_f32_16x16x32_bf16 v[118:121], v[140:143], v[188:191], v[118:121]
	v_mfma_f32_16x16x32_bf16 v[114:117], v[148:151], v[188:191], v[114:117]
	v_mfma_f32_16x16x32_bf16 v[110:113], v[140:143], v[196:199], v[110:113]
	v_mfma_f32_16x16x32_bf16 v[106:109], v[148:151], v[196:199], v[106:109]
	v_mfma_f32_16x16x32_bf16 v[102:105], v[140:143], v[204:207], v[102:105]
	v_mfma_f32_16x16x32_bf16 v[98:101], v[148:151], v[204:207], v[98:101]
	v_mfma_f32_16x16x32_bf16 v[126:129], v[144:147], v[184:187], v[126:129]
	v_mfma_f32_16x16x32_bf16 v[122:125], v[152:155], v[184:187], v[122:125]
	v_mfma_f32_16x16x32_bf16 v[118:121], v[144:147], v[192:195], v[118:121]
	v_mfma_f32_16x16x32_bf16 v[114:117], v[152:155], v[192:195], v[114:117]
	v_mfma_f32_16x16x32_bf16 v[110:113], v[144:147], v[200:203], v[110:113]
	v_mfma_f32_16x16x32_bf16 v[106:109], v[152:155], v[200:203], v[106:109]
	v_mfma_f32_16x16x32_bf16 v[102:105], v[144:147], v[208:211], v[102:105]
	v_mfma_f32_16x16x32_bf16 v[98:101], v[152:155], v[208:211], v[98:101]
	s_setprio 0
	s_setprio 1
	v_mfma_f32_16x16x32_bf16 v[94:97], v[156:159], v[180:183], v[94:97]
	v_mfma_f32_16x16x32_bf16 v[90:93], v[164:167], v[180:183], v[90:93]
	v_mfma_f32_16x16x32_bf16 v[86:89], v[156:159], v[188:191], v[86:89]
	v_mfma_f32_16x16x32_bf16 v[82:85], v[164:167], v[188:191], v[82:85]
	v_mfma_f32_16x16x32_bf16 v[78:81], v[156:159], v[196:199], v[78:81]
	v_mfma_f32_16x16x32_bf16 v[74:77], v[164:167], v[196:199], v[74:77]
	v_mfma_f32_16x16x32_bf16 v[70:73], v[156:159], v[204:207], v[70:73]
	v_mfma_f32_16x16x32_bf16 v[66:69], v[164:167], v[204:207], v[66:69]
	v_mfma_f32_16x16x32_bf16 v[94:97], v[160:163], v[184:187], v[94:97]
	v_mfma_f32_16x16x32_bf16 v[90:93], v[176:179], v[184:187], v[90:93]
	v_mfma_f32_16x16x32_bf16 v[86:89], v[160:163], v[192:195], v[86:89]
	v_mfma_f32_16x16x32_bf16 v[82:85], v[176:179], v[192:195], v[82:85]
	v_mfma_f32_16x16x32_bf16 v[78:81], v[160:163], v[200:203], v[78:81]
	v_mfma_f32_16x16x32_bf16 v[74:77], v[176:179], v[200:203], v[74:77]
	v_mfma_f32_16x16x32_bf16 v[70:73], v[160:163], v[208:211], v[70:73]
	v_mfma_f32_16x16x32_bf16 v[66:69], v[176:179], v[208:211], v[66:69]
	s_setprio 0
	s_barrier
; #define PG8_STAGE(bufoff, gbase, voff) do { _Pragma("unroll") for (int _i = 0; _i < 2; ++_i) \
;         __builtin_amdgcn_global_load_lds((const unsigned*)((const char*)(gbase) + (voff)[_i]), (LAS unsigned*)(lds + (bufoff) + ldsw + _i * 8192), 16, 0, 0); } while (0)
; #define PG8_LDA(dst, b, h) do { _Pragma("unroll") for (int m = 0; m < 4; ++m) _Pragma("unroll") for (int k = 0; k < 2; ++k) dst[m][k] = *(const LAS bf16x8*)(lds + PG8_SA(b, h) + aoff + m * 2048 + k * 1024); } while (0)
; #define PG8_MMA(ai, bj, At, Bt) do { __builtin_amdgcn_s_setprio(1); _Pragma("unroll") for (int m = 0; m < 4; ++m) _Pragma("unroll") for (int n = 0; n < 2; ++n) _Pragma("unroll") for (int k = 0; k < 2; ++k) \
;         acc[ai][bj][m][n] = __builtin_amdgcn_mfma_f32_16x16x32_bf16(Bt[n][k], At[m][k], acc[ai][bj][m][n], 0, 0, 0); __builtin_amdgcn_s_setprio(0); } while (0)
; #define PG8_WAIT_V(n) asm volatile("s_waitcnt vmcnt(" #n ")" ::: "memory")
; #define PG8_WAIT_L(n) asm volatile("s_waitcnt lgkmcnt(" #n ")" ::: "memory")
; #define PG8_BAR __builtin_amdgcn_s_barrier()
; #define PG8_SCHED __builtin_amdgcn_sched_barrier(0)
; template <class Epi, class Sched, int NSEG, int KK, int LDA, int LDB>
; __device__ __forceinline__ void gemm_phase(LAS unsigned char* lds, const Gemm g, const Sched& S, const Epi& E) {
;     ...
;             PG8_LDA(At, 1, 1); PG8_STAGE(PG8_SB(1, 0), b3, voffB); PG8_STAGE(PG8_SB(1, 1), b3 + hstepB, voffB); PG8_STAGE(PG8_SA(1, 0), a3, voffA);
;             PG8_WAIT_V(8); PG8_WAIT_L(0); PG8_BAR; PG8_MMA(1, 0, At, B0); PG8_MMA(1, 1, At, B1); PG8_BAR; PG8_SCHED;
;         }
;         if (wr == 0) PG8_BAR;
	s_add_i32 s8, s83, s53
	v_lshl_add_u64 v[212:213], v[212:213], 0, s[28:29]
	s_mov_b32 m0, s8
	ds_read_b128 v[180:183], v245 offset:49152
	ds_read_b128 v[184:187], v245 offset:50176
	ds_read_b128 v[188:191], v245 offset:51200
	ds_read_b128 v[192:195], v245 offset:52224
	ds_read_b128 v[196:199], v245 offset:53248
	ds_read_b128 v[200:203], v245 offset:54272
	ds_read_b128 v[204:207], v245 offset:55296
	ds_read_b128 v[208:211], v245 offset:56320
	global_load_lds_dwordx4 v[212:213], off
	s_add_i32 m0, s8, 0x2000
	s_add_u32 s8, s10, 0x20080
	v_lshl_add_u64 v[212:213], v[214:215], 0, s[28:29]
	s_addc_u32 s9, s11, 0
	s_add_i32 s10, s91, s53
	global_load_lds_dwordx4 v[212:213], off
	v_lshl_add_u64 v[212:213], s[8:9], 0, v[0:1]
	s_mov_b32 m0, s10
	s_nop 0
	global_load_lds_dwordx4 v[212:213], off
	v_lshl_add_u64 v[212:213], s[8:9], 0, v[130:131]
	s_add_i32 m0, s10, 0x2000
	s_nop 0
	global_load_lds_dwordx4 v[212:213], off
	v_lshl_add_u64 v[212:213], v[216:217], 0, s[28:29]
	s_mov_b32 m0, s59
	s_nop 0
	global_load_lds_dwordx4 v[212:213], off
	v_lshl_add_u64 v[212:213], v[218:219], 0, s[28:29]
	s_mov_b32 m0, s60
	s_nop 0
	global_load_lds_dwordx4 v[212:213], off
	s_waitcnt vmcnt(8)
	s_waitcnt lgkmcnt(0)
	s_barrier
	s_setprio 1
	v_mfma_f32_16x16x32_bf16 v[62:65], v[140:143], v[180:183], v[62:65]
	v_mfma_f32_16x16x32_bf16 v[58:61], v[148:151], v[180:183], v[58:61]
	v_mfma_f32_16x16x32_bf16 v[54:57], v[140:143], v[188:191], v[54:57]
	v_mfma_f32_16x16x32_bf16 v[50:53], v[148:151], v[188:191], v[50:53]
	v_mfma_f32_16x16x32_bf16 v[46:49], v[140:143], v[196:199], v[46:49]
	v_mfma_f32_16x16x32_bf16 v[42:45], v[148:151], v[196:199], v[42:45]
	v_mfma_f32_16x16x32_bf16 v[38:41], v[140:143], v[204:207], v[38:41]
	v_mfma_f32_16x16x32_bf16 v[34:37], v[148:151], v[204:207], v[34:37]
	v_mfma_f32_16x16x32_bf16 v[62:65], v[144:147], v[184:187], v[62:65]
	v_mfma_f32_16x16x32_bf16 v[58:61], v[152:155], v[184:187], v[58:61]
	v_mfma_f32_16x16x32_bf16 v[54:57], v[144:147], v[192:195], v[54:57]
	v_mfma_f32_16x16x32_bf16 v[50:53], v[152:155], v[192:195], v[50:53]
	v_mfma_f32_16x16x32_bf16 v[46:49], v[144:147], v[200:203], v[46:49]
	v_mfma_f32_16x16x32_bf16 v[42:45], v[152:155], v[200:203], v[42:45]
	v_mfma_f32_16x16x32_bf16 v[38:41], v[144:147], v[208:211], v[38:41]
	v_mfma_f32_16x16x32_bf16 v[34:37], v[152:155], v[208:211], v[34:37]
	s_setprio 0
	s_setprio 1
	v_mfma_f32_16x16x32_bf16 v[30:33], v[156:159], v[180:183], v[30:33]
	v_mfma_f32_16x16x32_bf16 v[26:29], v[164:167], v[180:183], v[26:29]
	v_mfma_f32_16x16x32_bf16 v[22:25], v[156:159], v[188:191], v[22:25]
	v_mfma_f32_16x16x32_bf16 v[18:21], v[164:167], v[188:191], v[18:21]
	v_mfma_f32_16x16x32_bf16 v[14:17], v[156:159], v[196:199], v[14:17]
	v_mfma_f32_16x16x32_bf16 v[10:13], v[164:167], v[196:199], v[10:13]
	v_mfma_f32_16x16x32_bf16 v[6:9], v[156:159], v[204:207], v[6:9]
	v_mfma_f32_16x16x32_bf16 v[2:5], v[164:167], v[204:207], v[2:5]
	v_mfma_f32_16x16x32_bf16 v[30:33], v[160:163], v[184:187], v[30:33]
	v_mfma_f32_16x16x32_bf16 v[26:29], v[176:179], v[184:187], v[26:29]
	v_mfma_f32_16x16x32_bf16 v[22:25], v[160:163], v[192:195], v[22:25]
	v_mfma_f32_16x16x32_bf16 v[18:21], v[176:179], v[192:195], v[18:21]
	v_mfma_f32_16x16x32_bf16 v[14:17], v[160:163], v[200:203], v[14:17]
	v_mfma_f32_16x16x32_bf16 v[10:13], v[176:179], v[200:203], v[10:13]
	v_mfma_f32_16x16x32_bf16 v[6:9], v[160:163], v[208:211], v[6:9]
	v_mfma_f32_16x16x32_bf16 v[2:5], v[176:179], v[208:211], v[2:5]
	s_setprio 0
	s_barrier
	s_add_i32 s77, s77, 2
	s_add_u32 s49, s49, 0x100
	s_addc_u32 s63, s63, 0
	s_cmp_gt_u32 s77, 5
	s_mov_b64 s[8:9], s[42:43]
	s_cbranch_scc0 .LBB0_759
	s_mov_b32 s101, 1
	s_and_b64 vcc, exec, s[46:47]
	s_cbranch_vccz .LBB0_762
	s_barrier

; #define PG8_STAGE(bufoff, gbase, voff) do { _Pragma("unroll") for (int _i = 0; _i < 2; ++_i) \
;         __builtin_amdgcn_global_load_lds((const unsigned*)((const char*)(gbase) + (voff)[_i]), (LAS unsigned*)(lds + (bufoff) + ldsw + _i * 8192), 16, 0, 0); } while (0)
; #define PG8_LDA(dst, b, h) do { _Pragma("unroll") for (int m = 0; m < 4; ++m) _Pragma("unroll") for (int k = 0; k < 2; ++k) dst[m][k] = *(const LAS bf16x8*)(lds + PG8_SA(b, h) + aoff + m * 2048 + k * 1024); } while (0)
; #define PG8_MMA(ai, bj, At, Bt) do { __builtin_amdgcn_s_setprio(1); _Pragma("unroll") for (int m = 0; m < 4; ++m) _Pragma("unroll") for (int n = 0; n < 2; ++n) _Pragma("unroll") for (int k = 0; k < 2; ++k) \
;         acc[ai][bj][m][n] = __builtin_amdgcn_mfma_f32_16x16x32_bf16(Bt[n][k], At[m][k], acc[ai][bj][m][n], 0, 0, 0); __builtin_amdgcn_s_setprio(0); } while (0)
; #define PG8_WAIT_V(n) asm volatile("s_waitcnt vmcnt(" #n ")" ::: "memory")
; #define PG8_WAIT_L(n) asm volatile("s_waitcnt lgkmcnt(" #n ")" ::: "memory")
; #define PG8_BAR __builtin_amdgcn_s_barrier()
; #define PG8_SCHED __builtin_amdgcn_sched_barrier(0)
; template <class Epi, class Sched, int NSEG, int KK, int LDA, int LDB>
; __device__ __forceinline__ void gemm_phase(LAS unsigned char* lds, const Gemm g, const Sched& S, const Epi& E) {
;     ...
;             PG8_WAIT_V(8); PG8_WAIT_L(0); PG8_BAR; PG8_MMA(0, 0, At, B0); PG8_MMA(0, 1, At, B1); PG8_BAR; PG8_SCHED;
;             PG8_LDA(At, 0, 1); PG8_STAGE(PG8_SB(0, 0), b2, voffB); PG8_STAGE(PG8_SB(0, 1), b2 + hstepB, voffB); PG8_STAGE(PG8_SA(0, 0), a2, voffA);
;             PG8_WAIT_V(8); PG8_WAIT_L(0); PG8_BAR; PG8_MMA(1, 0, At, B0); PG8_MMA(1, 1, At, B1); PG8_BAR; PG8_SCHED;
.Lskw_3_1:
	s_waitcnt lgkmcnt(0)
	s_barrier
	s_setprio 1
	v_mfma_f32_16x16x32_bf16 v[126:129], v[136:139], v[180:183], v[126:129]
	v_mfma_f32_16x16x32_bf16 v[122:125], v[144:147], v[180:183], v[122:125]
	v_mfma_f32_16x16x32_bf16 v[110:113], v[136:139], v[188:191], v[110:113]
	v_mfma_f32_16x16x32_bf16 v[106:109], v[144:147], v[188:191], v[106:109]
	v_mfma_f32_16x16x32_bf16 v[94:97], v[136:139], v[196:199], v[94:97]
	v_mfma_f32_16x16x32_bf16 v[90:93], v[144:147], v[196:199], v[90:93]
	v_mfma_f32_16x16x32_bf16 v[78:81], v[136:139], v[204:207], v[78:81]
	v_mfma_f32_16x16x32_bf16 v[74:77], v[144:147], v[204:207], v[74:77]
	v_mfma_f32_16x16x32_bf16 v[126:129], v[140:143], v[184:187], v[126:129]
	v_mfma_f32_16x16x32_bf16 v[122:125], v[148:151], v[184:187], v[122:125]
	v_mfma_f32_16x16x32_bf16 v[110:113], v[140:143], v[192:195], v[110:113]
	v_mfma_f32_16x16x32_bf16 v[106:109], v[148:151], v[192:195], v[106:109]
	v_mfma_f32_16x16x32_bf16 v[94:97], v[140:143], v[200:203], v[94:97]
	v_mfma_f32_16x16x32_bf16 v[90:93], v[148:151], v[200:203], v[90:93]
	v_mfma_f32_16x16x32_bf16 v[78:81], v[140:143], v[208:211], v[78:81]
	v_mfma_f32_16x16x32_bf16 v[74:77], v[148:151], v[208:211], v[74:77]
	s_setprio 0
	s_setprio 1
	v_mfma_f32_16x16x32_bf16 v[118:121], v[152:155], v[180:183], v[118:121]
	v_mfma_f32_16x16x32_bf16 v[114:117], v[160:163], v[180:183], v[114:117]
	v_mfma_f32_16x16x32_bf16 v[102:105], v[152:155], v[188:191], v[102:105]
	v_mfma_f32_16x16x32_bf16 v[98:101], v[160:163], v[188:191], v[98:101]
	v_mfma_f32_16x16x32_bf16 v[86:89], v[152:155], v[196:199], v[86:89]
	v_mfma_f32_16x16x32_bf16 v[82:85], v[160:163], v[196:199], v[82:85]
	v_mfma_f32_16x16x32_bf16 v[70:73], v[152:155], v[204:207], v[70:73]
	v_mfma_f32_16x16x32_bf16 v[66:69], v[160:163], v[204:207], v[66:69]
	v_mfma_f32_16x16x32_bf16 v[118:121], v[156:159], v[184:187], v[118:121]
	v_mfma_f32_16x16x32_bf16 v[114:117], v[176:179], v[184:187], v[114:117]
	v_mfma_f32_16x16x32_bf16 v[102:105], v[156:159], v[192:195], v[102:105]
	v_mfma_f32_16x16x32_bf16 v[98:101], v[176:179], v[192:195], v[98:101]
	v_mfma_f32_16x16x32_bf16 v[86:89], v[156:159], v[200:203], v[86:89]
	v_mfma_f32_16x16x32_bf16 v[82:85], v[176:179], v[200:203], v[82:85]
	v_mfma_f32_16x16x32_bf16 v[70:73], v[156:159], v[208:211], v[70:73]
	v_mfma_f32_16x16x32_bf16 v[66:69], v[176:179], v[208:211], v[66:69]
	s_setprio 0
	s_barrier
	s_add_i32 s63, s63, s23
	v_lshl_add_u64 v[166:167], s[10:11], 0, v[0:1]
	s_mov_b32 m0, s63
	ds_read_b128 v[180:183], v165 offset:16384
	ds_read_b128 v[184:187], v165 offset:17408
	ds_read_b128 v[188:191], v165 offset:18432
	ds_read_b128 v[192:195], v165 offset:19456
	ds_read_b128 v[196:199], v165 offset:20480
	ds_read_b128 v[200:203], v165 offset:21504
	ds_read_b128 v[204:207], v165 offset:22528
	ds_read_b128 v[208:211], v165 offset:23552
	global_load_lds_dwordx4 v[166:167], off
	s_add_i32 m0, s63, 0x2000
	s_add_u32 s94, s10, 0x40000
	v_lshl_add_u64 v[172:173], s[10:11], 0, v[130:131]
	s_addc_u32 s95, s11, 0
	s_add_i32 s63, s77, s23
	global_load_lds_dwordx4 v[172:173], off
	v_lshl_add_u64 v[212:213], s[94:95], 0, v[0:1]
	s_mov_b32 m0, s63
	v_lshl_add_u64 v[214:215], s[44:45], 0, v[130:131]
	global_load_lds_dwordx4 v[212:213], off
	v_lshl_add_u64 v[212:213], s[94:95], 0, v[130:131]
	s_add_i32 m0, s63, 0x2000
	s_nop 0
	global_load_lds_dwordx4 v[212:213], off
	v_lshl_add_u64 v[212:213], s[44:45], 0, v[0:1]
	s_mov_b32 m0, s26
	s_nop 0
	global_load_lds_dwordx4 v[212:213], off
	s_mov_b32 m0, s33
	s_nop 0
	global_load_lds_dwordx4 v[214:215], off
	s_cmp_lg_u32 s101, 0
	s_cbranch_scc1 .Lskw_3_2
	s_waitcnt vmcnt(8)
.Lskw_3_2:
	s_mov_b32 s101, 0
	s_waitcnt lgkmcnt(0)
	s_barrier
	s_setprio 1
	v_mfma_f32_16x16x32_bf16 v[62:65], v[136:139], v[180:183], v[62:65]
	v_mfma_f32_16x16x32_bf16 v[58:61], v[144:147], v[180:183], v[58:61]
	v_mfma_f32_16x16x32_bf16 v[46:49], v[136:139], v[188:191], v[46:49]
	v_mfma_f32_16x16x32_bf16 v[42:45], v[144:147], v[188:191], v[42:45]
	v_mfma_f32_16x16x32_bf16 v[30:33], v[136:139], v[196:199], v[30:33]
	v_mfma_f32_16x16x32_bf16 v[26:29], v[144:147], v[196:199], v[26:29]
	v_mfma_f32_16x16x32_bf16 v[14:17], v[136:139], v[204:207], v[14:17]
	v_mfma_f32_16x16x32_bf16 v[10:13], v[144:147], v[204:207], v[10:13]
	v_mfma_f32_16x16x32_bf16 v[62:65], v[140:143], v[184:187], v[62:65]
	v_mfma_f32_16x16x32_bf16 v[58:61], v[148:151], v[184:187], v[58:61]
	v_mfma_f32_16x16x32_bf16 v[46:49], v[140:143], v[192:195], v[46:49]
	v_mfma_f32_16x16x32_bf16 v[42:45], v[148:151], v[192:195], v[42:45]
	v_mfma_f32_16x16x32_bf16 v[30:33], v[140:143], v[200:203], v[30:33]
	v_mfma_f32_16x16x32_bf16 v[26:29], v[148:151], v[200:203], v[26:29]
	v_mfma_f32_16x16x32_bf16 v[14:17], v[140:143], v[208:211], v[14:17]
	v_mfma_f32_16x16x32_bf16 v[10:13], v[148:151], v[208:211], v[10:13]
	s_setprio 0
	s_setprio 1
	v_mfma_f32_16x16x32_bf16 v[54:57], v[152:155], v[180:183], v[54:57]
	v_mfma_f32_16x16x32_bf16 v[50:53], v[160:163], v[180:183], v[50:53]
	v_mfma_f32_16x16x32_bf16 v[38:41], v[152:155], v[188:191], v[38:41]
	v_mfma_f32_16x16x32_bf16 v[34:37], v[160:163], v[188:191], v[34:37]
	v_mfma_f32_16x16x32_bf16 v[22:25], v[152:155], v[196:199], v[22:25]
	v_mfma_f32_16x16x32_bf16 v[18:21], v[160:163], v[196:199], v[18:21]
	v_mfma_f32_16x16x32_bf16 v[6:9], v[152:155], v[204:207], v[6:9]
	v_mfma_f32_16x16x32_bf16 v[2:5], v[160:163], v[204:207], v[2:5]
	v_mfma_f32_16x16x32_bf16 v[54:57], v[156:159], v[184:187], v[54:57]
	v_mfma_f32_16x16x32_bf16 v[50:53], v[176:179], v[184:187], v[50:53]
	v_mfma_f32_16x16x32_bf16 v[38:41], v[156:159], v[192:195], v[38:41]
	v_mfma_f32_16x16x32_bf16 v[34:37], v[176:179], v[192:195], v[34:37]
	v_mfma_f32_16x16x32_bf16 v[22:25], v[156:159], v[200:203], v[22:25]
	v_mfma_f32_16x16x32_bf16 v[18:21], v[176:179], v[200:203], v[18:21]
	v_mfma_f32_16x16x32_bf16 v[6:9], v[156:159], v[208:211], v[6:9]
	v_mfma_f32_16x16x32_bf16 v[2:5], v[176:179], v[208:211], v[2:5]
	s_setprio 0
	s_barrier
; #define PG8_STAGE(bufoff, gbase, voff) do { _Pragma("unroll") for (int _i = 0; _i < 2; ++_i) \
;         __builtin_amdgcn_global_load_lds((const unsigned*)((const char*)(gbase) + (voff)[_i]), (LAS unsigned*)(lds + (bufoff) + ldsw + _i * 8192), 16, 0, 0); } while (0)
; #define PG8_LDA(dst, b, h) do { _Pragma("unroll") for (int m = 0; m < 4; ++m) _Pragma("unroll") for (int k = 0; k < 2; ++k) dst[m][k] = *(const LAS bf16x8*)(lds + PG8_SA(b, h) + aoff + m * 2048 + k * 1024); } while (0)
; #define PG8_LDB(dst, b, h) do { _Pragma("unroll") for (int n = 0; n < 2; ++n) _Pragma("unroll") for (int k = 0; k < 2; ++k) dst[n][k] = *(const LAS bf16x8*)(lds + PG8_SB(b, h) + boff + n * 2048 + k * 1024); } while (0)
; #define PG8_MMA(ai, bj, At, Bt) do { __builtin_amdgcn_s_setprio(1); _Pragma("unroll") for (int m = 0; m < 4; ++m) _Pragma("unroll") for (int n = 0; n < 2; ++n) _Pragma("unroll") for (int k = 0; k < 2; ++k) \
;         acc[ai][bj][m][n] = __builtin_amdgcn_mfma_f32_16x16x32_bf16(Bt[n][k], At[m][k], acc[ai][bj][m][n], 0, 0, 0); __builtin_amdgcn_s_setprio(0); } while (0)
; #define PG8_WAIT_V(n) asm volatile("s_waitcnt vmcnt(" #n ")" ::: "memory")
; #define PG8_WAIT_L(n) asm volatile("s_waitcnt lgkmcnt(" #n ")" ::: "memory")
; #define PG8_BAR __builtin_amdgcn_s_barrier()
; #define PG8_SCHED __builtin_amdgcn_sched_barrier(0)
; template <class Epi, class Sched, int NSEG, int KK, int LDA, int LDB>
; __device__ __forceinline__ void gemm_phase(LAS unsigned char* lds, const Gemm g, const Sched& S, const Epi& E) {
;     ...
;             PG8_LDB(B0, 1, 0); PG8_LDB(B1, 1, 1); PG8_SCHED; PG8_LDA(At, 1, 0); PG8_STAGE(PG8_SA(0, 1), a2 + hstepA, voffA);
;             PG8_WAIT_V(8); PG8_WAIT_L(0); PG8_BAR; PG8_MMA(0, 0, At, B0); PG8_MMA(0, 1, At, B1); PG8_BAR; PG8_SCHED;
	s_add_i32 s63, 0, 0x18000
	s_add_i32 s77, 0, 0x1c000
	v_add_u32_e32 v148, s63, v164
	v_add_u32_e32 v176, s77, v164
	ds_read_b128 v[136:139], v148
	ds_read_b128 v[140:143], v148 offset:1024
	ds_read_b128 v[144:147], v148 offset:256
	ds_read_b128 v[148:151], v148 offset:1280
	ds_read_b128 v[152:155], v176
	ds_read_b128 v[156:159], v176 offset:1024
	ds_read_b128 v[160:163], v176 offset:256
	ds_read_b128 v[176:179], v176 offset:1280
	s_add_u32 s44, s44, 0x40000
	s_addc_u32 s45, s45, 0
	s_mov_b32 m0, s38
	v_lshl_add_u64 v[216:217], s[44:45], 0, v[0:1]
	ds_read_b128 v[180:183], v165 offset:32768
	ds_read_b128 v[184:187], v165 offset:33792
	ds_read_b128 v[188:191], v165 offset:34816
	ds_read_b128 v[192:195], v165 offset:35840
	ds_read_b128 v[196:199], v165 offset:36864
	ds_read_b128 v[200:203], v165 offset:37888
	ds_read_b128 v[204:207], v165 offset:38912
	ds_read_b128 v[208:211], v165 offset:39936
	global_load_lds_dwordx4 v[216:217], off
	v_lshl_add_u64 v[216:217], s[44:45], 0, v[130:131]
	s_mov_b32 m0, s39
	s_nop 0
	global_load_lds_dwordx4 v[216:217], off
	s_waitcnt vmcnt(8)
	s_waitcnt lgkmcnt(0)
	s_barrier
	s_setprio 1
	v_mfma_f32_16x16x32_bf16 v[126:129], v[136:139], v[180:183], v[126:129]
	v_mfma_f32_16x16x32_bf16 v[122:125], v[144:147], v[180:183], v[122:125]
	v_mfma_f32_16x16x32_bf16 v[110:113], v[136:139], v[188:191], v[110:113]
	v_mfma_f32_16x16x32_bf16 v[106:109], v[144:147], v[188:191], v[106:109]
	v_mfma_f32_16x16x32_bf16 v[94:97], v[136:139], v[196:199], v[94:97]
	v_mfma_f32_16x16x32_bf16 v[90:93], v[144:147], v[196:199], v[90:93]
	v_mfma_f32_16x16x32_bf16 v[78:81], v[136:139], v[204:207], v[78:81]
	v_mfma_f32_16x16x32_bf16 v[74:77], v[144:147], v[204:207], v[74:77]
	v_mfma_f32_16x16x32_bf16 v[126:129], v[140:143], v[184:187], v[126:129]
	v_mfma_f32_16x16x32_bf16 v[122:125], v[148:151], v[184:187], v[122:125]
	v_mfma_f32_16x16x32_bf16 v[110:113], v[140:143], v[192:195], v[110:113]
	v_mfma_f32_16x16x32_bf16 v[106:109], v[148:151], v[192:195], v[106:109]
	v_mfma_f32_16x16x32_bf16 v[94:97], v[140:143], v[200:203], v[94:97]
	v_mfma_f32_16x16x32_bf16 v[90:93], v[148:151], v[200:203], v[90:93]
	v_mfma_f32_16x16x32_bf16 v[78:81], v[140:143], v[208:211], v[78:81]
	v_mfma_f32_16x16x32_bf16 v[74:77], v[148:151], v[208:211], v[74:77]
	s_setprio 0
	s_setprio 1
	v_mfma_f32_16x16x32_bf16 v[118:121], v[152:155], v[180:183], v[118:121]
	v_mfma_f32_16x16x32_bf16 v[114:117], v[160:163], v[180:183], v[114:117]
	v_mfma_f32_16x16x32_bf16 v[102:105], v[152:155], v[188:191], v[102:105]
	v_mfma_f32_16x16x32_bf16 v[98:101], v[160:163], v[188:191], v[98:101]
	v_mfma_f32_16x16x32_bf16 v[86:89], v[152:155], v[196:199], v[86:89]
	v_mfma_f32_16x16x32_bf16 v[82:85], v[160:163], v[196:199], v[82:85]
	v_mfma_f32_16x16x32_bf16 v[70:73], v[152:155], v[204:207], v[70:73]
	v_mfma_f32_16x16x32_bf16 v[66:69], v[160:163], v[204:207], v[66:69]
	v_mfma_f32_16x16x32_bf16 v[118:121], v[156:159], v[184:187], v[118:121]
	v_mfma_f32_16x16x32_bf16 v[114:117], v[176:179], v[184:187], v[114:117]
	v_mfma_f32_16x16x32_bf16 v[102:105], v[156:159], v[192:195], v[102:105]
	v_mfma_f32_16x16x32_bf16 v[98:101], v[176:179], v[192:195], v[98:101]
	v_mfma_f32_16x16x32_bf16 v[86:89], v[156:159], v[200:203], v[86:89]
	v_mfma_f32_16x16x32_bf16 v[82:85], v[176:179], v[200:203], v[82:85]
	v_mfma_f32_16x16x32_bf16 v[70:73], v[156:159], v[208:211], v[70:73]
	v_mfma_f32_16x16x32_bf16 v[66:69], v[176:179], v[208:211], v[66:69]
	s_setprio 0
	s_barrier
; #define PG8_STAGE(bufoff, gbase, voff) do { _Pragma("unroll") for (int _i = 0; _i < 2; ++_i) \
;         __builtin_amdgcn_global_load_lds((const unsigned*)((const char*)(gbase) + (voff)[_i]), (LAS unsigned*)(lds + (bufoff) + ldsw + _i * 8192), 16, 0, 0); } while (0)
; #define PG8_LDA(dst, b, h) do { _Pragma("unroll") for (int m = 0; m < 4; ++m) _Pragma("unroll") for (int k = 0; k < 2; ++k) dst[m][k] = *(const LAS bf16x8*)(lds + PG8_SA(b, h) + aoff + m * 2048 + k * 1024); } while (0)
; #define PG8_MMA(ai, bj, At, Bt) do { __builtin_amdgcn_s_setprio(1); _Pragma("unroll") for (int m = 0; m < 4; ++m) _Pragma("unroll") for (int n = 0; n < 2; ++n) _Pragma("unroll") for (int k = 0; k < 2; ++k) \
;         acc[ai][bj][m][n] = __builtin_amdgcn_mfma_f32_16x16x32_bf16(Bt[n][k], At[m][k], acc[ai][bj][m][n], 0, 0, 0); __builtin_amdgcn_s_setprio(0); } while (0)
; #define PG8_WAIT_V(n) asm volatile("s_waitcnt vmcnt(" #n ")" ::: "memory")
; #define PG8_WAIT_L(n) asm volatile("s_waitcnt lgkmcnt(" #n ")" ::: "memory")
; #define PG8_BAR __builtin_amdgcn_s_barrier()
; #define PG8_SCHED __builtin_amdgcn_sched_barrier(0)
; template <class Epi, class Sched, int NSEG, int KK, int LDA, int LDB>
; __device__ __forceinline__ void gemm_phase(LAS unsigned char* lds, const Gemm g, const Sched& S, const Epi& E) {
;     ...
;             PG8_LDA(At, 1, 1); PG8_STAGE(PG8_SB(1, 0), b3, voffB); PG8_STAGE(PG8_SB(1, 1), b3 + hstepB, voffB); PG8_STAGE(PG8_SA(1, 0), a3, voffA);
;             PG8_WAIT_V(8); PG8_WAIT_L(0); PG8_BAR; PG8_MMA(1, 0, At, B0); PG8_MMA(1, 1, At, B1); PG8_BAR; PG8_SCHED;
;         }
;         if (wr == 0) PG8_BAR;
	s_add_i32 s44, s63, s23
	v_lshl_add_u64 v[166:167], v[166:167], 0, s[28:29]
	s_mov_b32 m0, s44
	ds_read_b128 v[180:183], v165 offset:49152
	ds_read_b128 v[184:187], v165 offset:50176
	ds_read_b128 v[188:191], v165 offset:51200
	ds_read_b128 v[192:195], v165 offset:52224
	ds_read_b128 v[196:199], v165 offset:53248
	ds_read_b128 v[200:203], v165 offset:54272
	ds_read_b128 v[204:207], v165 offset:55296
	ds_read_b128 v[208:211], v165 offset:56320
	global_load_lds_dwordx4 v[166:167], off
	s_add_i32 m0, s44, 0x2000
	s_add_u32 s10, s10, 0x40080
	v_lshl_add_u64 v[166:167], v[172:173], 0, s[28:29]
	s_addc_u32 s11, s11, 0
	s_add_i32 s44, s77, s23
	global_load_lds_dwordx4 v[166:167], off
	v_lshl_add_u64 v[166:167], s[10:11], 0, v[0:1]
	s_mov_b32 m0, s44
	s_nop 0
	global_load_lds_dwordx4 v[166:167], off
	v_lshl_add_u64 v[166:167], s[10:11], 0, v[130:131]
	s_add_i32 m0, s44, 0x2000
	s_nop 0
	global_load_lds_dwordx4 v[166:167], off
	v_lshl_add_u64 v[166:167], v[212:213], 0, s[28:29]
	s_mov_b32 m0, s57
	s_nop 0
	global_load_lds_dwordx4 v[166:167], off
	v_lshl_add_u64 v[166:167], v[214:215], 0, s[28:29]
	s_mov_b32 m0, s58
	s_nop 0
	global_load_lds_dwordx4 v[166:167], off
	s_waitcnt vmcnt(8)
	s_waitcnt lgkmcnt(0)
	s_barrier
	s_setprio 1
	v_mfma_f32_16x16x32_bf16 v[62:65], v[136:139], v[180:183], v[62:65]
	v_mfma_f32_16x16x32_bf16 v[58:61], v[144:147], v[180:183], v[58:61]
	v_mfma_f32_16x16x32_bf16 v[46:49], v[136:139], v[188:191], v[46:49]
	v_mfma_f32_16x16x32_bf16 v[42:45], v[144:147], v[188:191], v[42:45]
	v_mfma_f32_16x16x32_bf16 v[30:33], v[136:139], v[196:199], v[30:33]
	v_mfma_f32_16x16x32_bf16 v[26:29], v[144:147], v[196:199], v[26:29]
	v_mfma_f32_16x16x32_bf16 v[14:17], v[136:139], v[204:207], v[14:17]
	v_mfma_f32_16x16x32_bf16 v[10:13], v[144:147], v[204:207], v[10:13]
	v_mfma_f32_16x16x32_bf16 v[62:65], v[140:143], v[184:187], v[62:65]
	v_mfma_f32_16x16x32_bf16 v[58:61], v[148:151], v[184:187], v[58:61]
	v_mfma_f32_16x16x32_bf16 v[46:49], v[140:143], v[192:195], v[46:49]
	v_mfma_f32_16x16x32_bf16 v[42:45], v[148:151], v[192:195], v[42:45]
	v_mfma_f32_16x16x32_bf16 v[30:33], v[140:143], v[200:203], v[30:33]
	v_mfma_f32_16x16x32_bf16 v[26:29], v[148:151], v[200:203], v[26:29]
	v_mfma_f32_16x16x32_bf16 v[14:17], v[140:143], v[208:211], v[14:17]
	v_mfma_f32_16x16x32_bf16 v[10:13], v[148:151], v[208:211], v[10:13]
	s_setprio 0
	s_setprio 1
	v_mfma_f32_16x16x32_bf16 v[54:57], v[152:155], v[180:183], v[54:57]
	v_mfma_f32_16x16x32_bf16 v[50:53], v[160:163], v[180:183], v[50:53]
	v_mfma_f32_16x16x32_bf16 v[38:41], v[152:155], v[188:191], v[38:41]
	v_mfma_f32_16x16x32_bf16 v[34:37], v[160:163], v[188:191], v[34:37]
	v_mfma_f32_16x16x32_bf16 v[22:25], v[152:155], v[196:199], v[22:25]
	v_mfma_f32_16x16x32_bf16 v[18:21], v[160:163], v[196:199], v[18:21]
	v_mfma_f32_16x16x32_bf16 v[6:9], v[152:155], v[204:207], v[6:9]
	v_mfma_f32_16x16x32_bf16 v[2:5], v[160:163], v[204:207], v[2:5]
	v_mfma_f32_16x16x32_bf16 v[54:57], v[156:159], v[184:187], v[54:57]
	v_mfma_f32_16x16x32_bf16 v[50:53], v[176:179], v[184:187], v[50:53]
	v_mfma_f32_16x16x32_bf16 v[38:41], v[156:159], v[192:195], v[38:41]
	v_mfma_f32_16x16x32_bf16 v[34:37], v[176:179], v[192:195], v[34:37]
	v_mfma_f32_16x16x32_bf16 v[22:25], v[156:159], v[200:203], v[22:25]
	v_mfma_f32_16x16x32_bf16 v[18:21], v[176:179], v[200:203], v[18:21]
	v_mfma_f32_16x16x32_bf16 v[6:9], v[156:159], v[208:211], v[6:9]
	v_mfma_f32_16x16x32_bf16 v[2:5], v[176:179], v[208:211], v[2:5]
	s_setprio 0
	s_barrier
	s_add_i32 s62, s62, 2
	s_add_u32 s42, s42, 0x100
	s_addc_u32 s43, s43, 0
	s_add_u32 s60, s60, 0x100
	s_addc_u32 s61, s61, 0
	s_cmp_gt_u32 s62, 13
	s_cbranch_scc0 .LBB0_985
	s_mov_b32 s101, 1
	s_and_b64 vcc, exec, s[8:9]
	s_cbranch_vccz .LBB0_988
	s_barrier

; #define PG8_STAGE(bufoff, gbase, voff) do { _Pragma("unroll") for (int _i = 0; _i < 2; ++_i) \
;         __builtin_amdgcn_global_load_lds((const unsigned*)((const char*)(gbase) + (voff)[_i]), (LAS unsigned*)(lds + (bufoff) + ldsw + _i * 8192), 16, 0, 0); } while (0)
; #define PG8_LDA(dst, b, h) do { _Pragma("unroll") for (int m = 0; m < 4; ++m) _Pragma("unroll") for (int k = 0; k < 2; ++k) dst[m][k] = *(const LAS bf16x8*)(lds + PG8_SA(b, h) + aoff + m * 2048 + k * 1024); } while (0)
; #define PG8_MMA(ai, bj, At, Bt) do { __builtin_amdgcn_s_setprio(1); _Pragma("unroll") for (int m = 0; m < 4; ++m) _Pragma("unroll") for (int n = 0; n < 2; ++n) _Pragma("unroll") for (int k = 0; k < 2; ++k) \
;         acc[ai][bj][m][n] = __builtin_amdgcn_mfma_f32_16x16x32_bf16(Bt[n][k], At[m][k], acc[ai][bj][m][n], 0, 0, 0); __builtin_amdgcn_s_setprio(0); } while (0)
; #define PG8_WAIT_V(n) asm volatile("s_waitcnt vmcnt(" #n ")" ::: "memory")
; #define PG8_WAIT_L(n) asm volatile("s_waitcnt lgkmcnt(" #n ")" ::: "memory")
; #define PG8_BAR __builtin_amdgcn_s_barrier()
; #define PG8_SCHED __builtin_amdgcn_sched_barrier(0)
; template <class Epi, class Sched, int NSEG, int KK, int LDA, int LDB>
; __device__ __forceinline__ void gemm_phase(LAS unsigned char* lds, const Gemm g, const Sched& S, const Epi& E) {
;     ...
;             PG8_WAIT_V(8); PG8_WAIT_L(0); PG8_BAR; PG8_MMA(0, 0, At, B0); PG8_MMA(0, 1, At, B1); PG8_BAR; PG8_SCHED;
;             PG8_LDA(At, 0, 1); PG8_STAGE(PG8_SB(0, 0), b2, voffB); PG8_STAGE(PG8_SB(0, 1), b2 + hstepB, voffB); PG8_STAGE(PG8_SA(0, 0), a2, voffA);
;             PG8_WAIT_V(8); PG8_WAIT_L(0); PG8_BAR; PG8_MMA(1, 0, At, B0); PG8_MMA(1, 1, At, B1); PG8_BAR; PG8_SCHED;
.Lskw_4_1:
	s_waitcnt lgkmcnt(0)
	s_barrier
	s_setprio 1
	v_mfma_f32_16x16x32_bf16 v[130:133], v[118:121], v[162:165], v[130:133]
	v_mfma_f32_16x16x32_bf16 v[126:129], v[138:141], v[162:165], v[126:129]
	v_mfma_f32_16x16x32_bf16 v[110:113], v[118:121], v[192:195], v[110:113]
	v_mfma_f32_16x16x32_bf16 v[46:49], v[138:141], v[192:195], v[46:49]
	v_mfma_f32_16x16x32_bf16 v[106:109], v[118:121], v[200:203], v[106:109]
	v_mfma_f32_16x16x32_bf16 v[42:45], v[138:141], v[200:203], v[42:45]
	v_mfma_f32_16x16x32_bf16 v[114:117], v[118:121], v[208:211], v[114:117]
	v_mfma_f32_16x16x32_bf16 v[50:53], v[138:141], v[208:211], v[50:53]
	v_mfma_f32_16x16x32_bf16 v[130:133], v[134:137], v[188:191], v[130:133]
	v_mfma_f32_16x16x32_bf16 v[126:129], v[142:145], v[188:191], v[126:129]
	v_mfma_f32_16x16x32_bf16 v[110:113], v[134:137], v[196:199], v[110:113]
	v_mfma_f32_16x16x32_bf16 v[46:49], v[142:145], v[196:199], v[46:49]
	v_mfma_f32_16x16x32_bf16 v[106:109], v[134:137], v[204:207], v[106:109]
	v_mfma_f32_16x16x32_bf16 v[42:45], v[142:145], v[204:207], v[42:45]
	v_mfma_f32_16x16x32_bf16 v[114:117], v[134:137], v[212:215], v[114:117]
	v_mfma_f32_16x16x32_bf16 v[50:53], v[142:145], v[212:215], v[50:53]
	s_setprio 0
	s_setprio 1
	v_mfma_f32_16x16x32_bf16 v[122:125], v[146:149], v[162:165], v[122:125]
	v_mfma_f32_16x16x32_bf16 v[62:65], v[154:157], v[162:165], v[62:65]
	v_mfma_f32_16x16x32_bf16 v[102:105], v[146:149], v[192:195], v[102:105]
	v_mfma_f32_16x16x32_bf16 v[38:41], v[154:157], v[192:195], v[38:41]
	v_mfma_f32_16x16x32_bf16 v[98:101], v[146:149], v[200:203], v[98:101]
	v_mfma_f32_16x16x32_bf16 v[34:37], v[154:157], v[200:203], v[34:37]
	v_mfma_f32_16x16x32_bf16 v[90:93], v[146:149], v[208:211], v[90:93]
	v_mfma_f32_16x16x32_bf16 v[54:57], v[154:157], v[208:211], v[54:57]
	v_mfma_f32_16x16x32_bf16 v[122:125], v[150:153], v[188:191], v[122:125]
	v_mfma_f32_16x16x32_bf16 v[62:65], v[158:161], v[188:191], v[62:65]
	v_mfma_f32_16x16x32_bf16 v[102:105], v[150:153], v[196:199], v[102:105]
	v_mfma_f32_16x16x32_bf16 v[38:41], v[158:161], v[196:199], v[38:41]
	v_mfma_f32_16x16x32_bf16 v[98:101], v[150:153], v[204:207], v[98:101]
	v_mfma_f32_16x16x32_bf16 v[34:37], v[158:161], v[204:207], v[34:37]
	v_mfma_f32_16x16x32_bf16 v[90:93], v[150:153], v[212:215], v[90:93]
	v_mfma_f32_16x16x32_bf16 v[54:57], v[158:161], v[212:215], v[54:57]
	s_setprio 0
	s_barrier
	s_add_i32 s55, s55, s38
	v_lshl_add_u64 v[172:173], s[10:11], 0, v[180:181]
	s_mov_b32 m0, s55
	ds_read_b128 v[162:165], v166 offset:16384
	ds_read_b128 v[188:191], v166 offset:17408
	ds_read_b128 v[192:195], v166 offset:18432
	ds_read_b128 v[196:199], v166 offset:19456
	ds_read_b128 v[200:203], v166 offset:20480
	ds_read_b128 v[204:207], v166 offset:21504
	ds_read_b128 v[208:211], v166 offset:22528
	ds_read_b128 v[212:215], v166 offset:23552
	global_load_lds_dwordx4 v[172:173], off
	s_add_i32 m0, s55, 0x2000
	s_add_u32 s60, s10, 0x40000
	v_lshl_add_u64 v[216:217], s[10:11], 0, v[176:177]
	s_addc_u32 s61, s11, 0
	s_add_i32 s55, s62, s38
	global_load_lds_dwordx4 v[216:217], off
	v_lshl_add_u64 v[218:219], s[60:61], 0, v[180:181]
	s_mov_b32 m0, s55
	v_lshl_add_u64 v[220:221], s[44:45], 0, v[178:179]
	global_load_lds_dwordx4 v[218:219], off
	v_lshl_add_u64 v[218:219], s[60:61], 0, v[176:177]
	s_add_i32 m0, s55, 0x2000
	s_nop 0
	global_load_lds_dwordx4 v[218:219], off
	v_lshl_add_u64 v[218:219], s[44:45], 0, v[182:183]
	s_mov_b32 m0, s39
	s_nop 0
	global_load_lds_dwordx4 v[218:219], off
	s_mov_b32 m0, s83
	s_nop 0
	global_load_lds_dwordx4 v[220:221], off
	s_cmp_lg_u32 s101, 0
	s_cbranch_scc1 .Lskw_4_2
	s_waitcnt vmcnt(8)
.Lskw_4_2:
	s_mov_b32 s101, 0
	s_waitcnt lgkmcnt(0)
	s_barrier
	s_setprio 1
	v_mfma_f32_16x16x32_bf16 v[94:97], v[118:121], v[162:165], v[94:97]
	v_mfma_f32_16x16x32_bf16 v[22:25], v[138:141], v[162:165], v[22:25]
	v_mfma_f32_16x16x32_bf16 v[86:89], v[118:121], v[192:195], v[86:89]
	v_mfma_f32_16x16x32_bf16 v[18:21], v[138:141], v[192:195], v[18:21]
	v_mfma_f32_16x16x32_bf16 v[74:77], v[118:121], v[200:203], v[74:77]
	v_mfma_f32_16x16x32_bf16 v[10:13], v[138:141], v[200:203], v[10:13]
	v_mfma_f32_16x16x32_bf16 v[82:85], v[118:121], v[208:211], v[82:85]
	v_mfma_f32_16x16x32_bf16 v[26:29], v[138:141], v[208:211], v[26:29]
	v_mfma_f32_16x16x32_bf16 v[94:97], v[134:137], v[188:191], v[94:97]
	v_mfma_f32_16x16x32_bf16 v[22:25], v[142:145], v[188:191], v[22:25]
	v_mfma_f32_16x16x32_bf16 v[86:89], v[134:137], v[196:199], v[86:89]
	v_mfma_f32_16x16x32_bf16 v[18:21], v[142:145], v[196:199], v[18:21]
	v_mfma_f32_16x16x32_bf16 v[74:77], v[134:137], v[204:207], v[74:77]
	v_mfma_f32_16x16x32_bf16 v[10:13], v[142:145], v[204:207], v[10:13]
	v_mfma_f32_16x16x32_bf16 v[82:85], v[134:137], v[212:215], v[82:85]
	v_mfma_f32_16x16x32_bf16 v[26:29], v[142:145], v[212:215], v[26:29]
	s_setprio 0
	s_setprio 1
	v_mfma_f32_16x16x32_bf16 v[78:81], v[146:149], v[162:165], v[78:81]
	v_mfma_f32_16x16x32_bf16 v[14:17], v[154:157], v[162:165], v[14:17]
	v_mfma_f32_16x16x32_bf16 v[70:73], v[146:149], v[192:195], v[70:73]
	v_mfma_f32_16x16x32_bf16 v[6:9], v[154:157], v[192:195], v[6:9]
	v_mfma_f32_16x16x32_bf16 v[66:69], v[146:149], v[200:203], v[66:69]
	v_mfma_f32_16x16x32_bf16 v[2:5], v[154:157], v[200:203], v[2:5]
	v_mfma_f32_16x16x32_bf16 v[58:61], v[146:149], v[208:211], v[58:61]
	v_mfma_f32_16x16x32_bf16 v[30:33], v[154:157], v[208:211], v[30:33]
	v_mfma_f32_16x16x32_bf16 v[78:81], v[150:153], v[188:191], v[78:81]
	v_mfma_f32_16x16x32_bf16 v[14:17], v[158:161], v[188:191], v[14:17]
	v_mfma_f32_16x16x32_bf16 v[70:73], v[150:153], v[196:199], v[70:73]
	v_mfma_f32_16x16x32_bf16 v[6:9], v[158:161], v[196:199], v[6:9]
	v_mfma_f32_16x16x32_bf16 v[66:69], v[150:153], v[204:207], v[66:69]
	v_mfma_f32_16x16x32_bf16 v[2:5], v[158:161], v[204:207], v[2:5]
	v_mfma_f32_16x16x32_bf16 v[58:61], v[150:153], v[212:215], v[58:61]
	v_mfma_f32_16x16x32_bf16 v[30:33], v[158:161], v[212:215], v[30:33]
	s_setprio 0
	s_barrier
; #define PG8_STAGE(bufoff, gbase, voff) do { _Pragma("unroll") for (int _i = 0; _i < 2; ++_i) \
;         __builtin_amdgcn_global_load_lds((const unsigned*)((const char*)(gbase) + (voff)[_i]), (LAS unsigned*)(lds + (bufoff) + ldsw + _i * 8192), 16, 0, 0); } while (0)
; #define PG8_LDA(dst, b, h) do { _Pragma("unroll") for (int m = 0; m < 4; ++m) _Pragma("unroll") for (int k = 0; k < 2; ++k) dst[m][k] = *(const LAS bf16x8*)(lds + PG8_SA(b, h) + aoff + m * 2048 + k * 1024); } while (0)
; #define PG8_LDB(dst, b, h) do { _Pragma("unroll") for (int n = 0; n < 2; ++n) _Pragma("unroll") for (int k = 0; k < 2; ++k) dst[n][k] = *(const LAS bf16x8*)(lds + PG8_SB(b, h) + boff + n * 2048 + k * 1024); } while (0)
; #define PG8_MMA(ai, bj, At, Bt) do { __builtin_amdgcn_s_setprio(1); _Pragma("unroll") for (int m = 0; m < 4; ++m) _Pragma("unroll") for (int n = 0; n < 2; ++n) _Pragma("unroll") for (int k = 0; k < 2; ++k) \
;         acc[ai][bj][m][n] = __builtin_amdgcn_mfma_f32_16x16x32_bf16(Bt[n][k], At[m][k], acc[ai][bj][m][n], 0, 0, 0); __builtin_amdgcn_s_setprio(0); } while (0)
; #define PG8_WAIT_V(n) asm volatile("s_waitcnt vmcnt(" #n ")" ::: "memory")
; #define PG8_WAIT_L(n) asm volatile("s_waitcnt lgkmcnt(" #n ")" ::: "memory")
; #define PG8_BAR __builtin_amdgcn_s_barrier()
; #define PG8_SCHED __builtin_amdgcn_sched_barrier(0)
; template <class Epi, class Sched, int NSEG, int KK, int LDA, int LDB>
; __device__ __forceinline__ void gemm_phase(LAS unsigned char* lds, const Gemm g, const Sched& S, const Epi& E) {
;     ...
;             PG8_LDB(B0, 1, 0); PG8_LDB(B1, 1, 1); PG8_SCHED; PG8_LDA(At, 1, 0); PG8_STAGE(PG8_SA(0, 1), a2 + hstepA, voffA);
;             PG8_WAIT_V(8); PG8_WAIT_L(0); PG8_BAR; PG8_MMA(0, 0, At, B0); PG8_MMA(0, 1, At, B1); PG8_BAR; PG8_SCHED;
	s_add_i32 s55, 0, 0x18000
	v_add_u32_e32 v0, s55, v252
	s_add_i32 s60, 0, 0x1c000
	ds_read_b128 v[118:121], v0
	ds_read_b128 v[134:137], v0 offset:1024
	ds_read_b128 v[138:141], v0 offset:2048
	ds_read_b128 v[142:145], v0 offset:3072
	v_add_u32_e32 v0, s60, v252
	ds_read_b128 v[146:149], v0
	ds_read_b128 v[150:153], v0 offset:1024
	ds_read_b128 v[154:157], v0 offset:2048
	ds_read_b128 v[158:161], v0 offset:3072
	s_add_u32 s44, s44, 0x40000
	s_addc_u32 s45, s45, 0
	s_mov_b32 m0, s77
	v_lshl_add_u64 v[222:223], s[44:45], 0, v[182:183]
	ds_read_b128 v[162:165], v166 offset:32768
	ds_read_b128 v[188:191], v166 offset:33792
	ds_read_b128 v[192:195], v166 offset:34816
	ds_read_b128 v[196:199], v166 offset:35840
	ds_read_b128 v[200:203], v166 offset:36864
	ds_read_b128 v[204:207], v166 offset:37888
	ds_read_b128 v[208:211], v166 offset:38912
	ds_read_b128 v[212:215], v166 offset:39936
	global_load_lds_dwordx4 v[222:223], off
	v_lshl_add_u64 v[222:223], s[44:45], 0, v[178:179]
	s_mov_b32 m0, s33
	s_nop 0
	global_load_lds_dwordx4 v[222:223], off
	s_waitcnt vmcnt(8)
	s_waitcnt lgkmcnt(0)
	s_barrier
	s_setprio 1
	v_mfma_f32_16x16x32_bf16 v[130:133], v[118:121], v[162:165], v[130:133]
	v_mfma_f32_16x16x32_bf16 v[126:129], v[138:141], v[162:165], v[126:129]
	v_mfma_f32_16x16x32_bf16 v[110:113], v[118:121], v[192:195], v[110:113]
	v_mfma_f32_16x16x32_bf16 v[46:49], v[138:141], v[192:195], v[46:49]
	v_mfma_f32_16x16x32_bf16 v[106:109], v[118:121], v[200:203], v[106:109]
	v_mfma_f32_16x16x32_bf16 v[42:45], v[138:141], v[200:203], v[42:45]
	v_mfma_f32_16x16x32_bf16 v[114:117], v[118:121], v[208:211], v[114:117]
	v_mfma_f32_16x16x32_bf16 v[50:53], v[138:141], v[208:211], v[50:53]
	v_mfma_f32_16x16x32_bf16 v[130:133], v[134:137], v[188:191], v[130:133]
	v_mfma_f32_16x16x32_bf16 v[126:129], v[142:145], v[188:191], v[126:129]
	v_mfma_f32_16x16x32_bf16 v[110:113], v[134:137], v[196:199], v[110:113]
	v_mfma_f32_16x16x32_bf16 v[46:49], v[142:145], v[196:199], v[46:49]
	v_mfma_f32_16x16x32_bf16 v[106:109], v[134:137], v[204:207], v[106:109]
	v_mfma_f32_16x16x32_bf16 v[42:45], v[142:145], v[204:207], v[42:45]
	v_mfma_f32_16x16x32_bf16 v[114:117], v[134:137], v[212:215], v[114:117]
	v_mfma_f32_16x16x32_bf16 v[50:53], v[142:145], v[212:215], v[50:53]
	s_setprio 0
	s_setprio 1
	v_mfma_f32_16x16x32_bf16 v[122:125], v[146:149], v[162:165], v[122:125]
	v_mfma_f32_16x16x32_bf16 v[62:65], v[154:157], v[162:165], v[62:65]
	v_mfma_f32_16x16x32_bf16 v[102:105], v[146:149], v[192:195], v[102:105]
	v_mfma_f32_16x16x32_bf16 v[38:41], v[154:157], v[192:195], v[38:41]
	v_mfma_f32_16x16x32_bf16 v[98:101], v[146:149], v[200:203], v[98:101]
	v_mfma_f32_16x16x32_bf16 v[34:37], v[154:157], v[200:203], v[34:37]
	v_mfma_f32_16x16x32_bf16 v[90:93], v[146:149], v[208:211], v[90:93]
	v_mfma_f32_16x16x32_bf16 v[54:57], v[154:157], v[208:211], v[54:57]
	v_mfma_f32_16x16x32_bf16 v[122:125], v[150:153], v[188:191], v[122:125]
	v_mfma_f32_16x16x32_bf16 v[62:65], v[158:161], v[188:191], v[62:65]
	v_mfma_f32_16x16x32_bf16 v[102:105], v[150:153], v[196:199], v[102:105]
	v_mfma_f32_16x16x32_bf16 v[38:41], v[158:161], v[196:199], v[38:41]
	v_mfma_f32_16x16x32_bf16 v[98:101], v[150:153], v[204:207], v[98:101]
	v_mfma_f32_16x16x32_bf16 v[34:37], v[158:161], v[204:207], v[34:37]
	v_mfma_f32_16x16x32_bf16 v[90:93], v[150:153], v[212:215], v[90:93]
	v_mfma_f32_16x16x32_bf16 v[54:57], v[158:161], v[212:215], v[54:57]
	s_setprio 0
	s_barrier
; #define PG8_STAGE(bufoff, gbase, voff) do { _Pragma("unroll") for (int _i = 0; _i < 2; ++_i) \
;         __builtin_amdgcn_global_load_lds((const unsigned*)((const char*)(gbase) + (voff)[_i]), (LAS unsigned*)(lds + (bufoff) + ldsw + _i * 8192), 16, 0, 0); } while (0)
; #define PG8_LDA(dst, b, h) do { _Pragma("unroll") for (int m = 0; m < 4; ++m) _Pragma("unroll") for (int k = 0; k < 2; ++k) dst[m][k] = *(const LAS bf16x8*)(lds + PG8_SA(b, h) + aoff + m * 2048 + k * 1024); } while (0)
; #define PG8_MMA(ai, bj, At, Bt) do { __builtin_amdgcn_s_setprio(1); _Pragma("unroll") for (int m = 0; m < 4; ++m) _Pragma("unroll") for (int n = 0; n < 2; ++n) _Pragma("unroll") for (int k = 0; k < 2; ++k) \
;         acc[ai][bj][m][n] = __builtin_amdgcn_mfma_f32_16x16x32_bf16(Bt[n][k], At[m][k], acc[ai][bj][m][n], 0, 0, 0); __builtin_amdgcn_s_setprio(0); } while (0)
; #define PG8_WAIT_V(n) asm volatile("s_waitcnt vmcnt(" #n ")" ::: "memory")
; #define PG8_WAIT_L(n) asm volatile("s_waitcnt lgkmcnt(" #n ")" ::: "memory")
; #define PG8_BAR __builtin_amdgcn_s_barrier()
; #define PG8_SCHED __builtin_amdgcn_sched_barrier(0)
; template <class Epi, class Sched, int NSEG, int KK, int LDA, int LDB>
; __device__ __forceinline__ void gemm_phase(LAS unsigned char* lds, const Gemm g, const Sched& S, const Epi& E) {
;     ...
;             PG8_LDA(At, 1, 1); PG8_STAGE(PG8_SB(1, 0), b3, voffB); PG8_STAGE(PG8_SB(1, 1), b3 + hstepB, voffB); PG8_STAGE(PG8_SA(1, 0), a3, voffA);
;             PG8_WAIT_V(8); PG8_WAIT_L(0); PG8_BAR; PG8_MMA(1, 0, At, B0); PG8_MMA(1, 1, At, B1); PG8_BAR; PG8_SCHED;
;         }
;         if (wr == 0) PG8_BAR;
	s_add_i32 s44, s55, s38
	v_lshl_add_u64 v[172:173], v[172:173], 0, s[28:29]
	s_mov_b32 m0, s44
	ds_read_b128 v[162:165], v166 offset:49152
	ds_read_b128 v[188:191], v166 offset:50176
	ds_read_b128 v[192:195], v166 offset:51200
	ds_read_b128 v[196:199], v166 offset:52224
	ds_read_b128 v[200:203], v166 offset:53248
	ds_read_b128 v[204:207], v166 offset:54272
	ds_read_b128 v[208:211], v166 offset:55296
	ds_read_b128 v[212:215], v166 offset:56320
	global_load_lds_dwordx4 v[172:173], off
	s_add_i32 m0, s44, 0x2000
	s_add_u32 s10, s10, 0x40080
	v_lshl_add_u64 v[172:173], v[216:217], 0, s[28:29]
	s_addc_u32 s11, s11, 0
	s_add_i32 s44, s60, s38
	global_load_lds_dwordx4 v[172:173], off
	v_lshl_add_u64 v[172:173], s[10:11], 0, v[180:181]
	s_mov_b32 m0, s44
	s_nop 0
	global_load_lds_dwordx4 v[172:173], off
	v_lshl_add_u64 v[172:173], s[10:11], 0, v[176:177]
	s_add_i32 m0, s44, 0x2000
	s_nop 0
	global_load_lds_dwordx4 v[172:173], off
	v_lshl_add_u64 v[172:173], v[218:219], 0, s[28:29]
	s_mov_b32 m0, s91
	s_nop 0
	global_load_lds_dwordx4 v[172:173], off
	v_lshl_add_u64 v[172:173], v[220:221], 0, s[28:29]
	s_mov_b32 m0, s94
	s_nop 0
	global_load_lds_dwordx4 v[172:173], off
	s_waitcnt vmcnt(8)
	s_waitcnt lgkmcnt(0)
	s_barrier
	s_setprio 1
	v_mfma_f32_16x16x32_bf16 v[94:97], v[118:121], v[162:165], v[94:97]
	v_mfma_f32_16x16x32_bf16 v[22:25], v[138:141], v[162:165], v[22:25]
	v_mfma_f32_16x16x32_bf16 v[86:89], v[118:121], v[192:195], v[86:89]
	v_mfma_f32_16x16x32_bf16 v[18:21], v[138:141], v[192:195], v[18:21]
	v_mfma_f32_16x16x32_bf16 v[74:77], v[118:121], v[200:203], v[74:77]
	v_mfma_f32_16x16x32_bf16 v[10:13], v[138:141], v[200:203], v[10:13]
	v_mfma_f32_16x16x32_bf16 v[82:85], v[118:121], v[208:211], v[82:85]
	v_mfma_f32_16x16x32_bf16 v[26:29], v[138:141], v[208:211], v[26:29]
	v_mfma_f32_16x16x32_bf16 v[94:97], v[134:137], v[188:191], v[94:97]
	v_mfma_f32_16x16x32_bf16 v[22:25], v[142:145], v[188:191], v[22:25]
	v_mfma_f32_16x16x32_bf16 v[86:89], v[134:137], v[196:199], v[86:89]
	v_mfma_f32_16x16x32_bf16 v[18:21], v[142:145], v[196:199], v[18:21]
	v_mfma_f32_16x16x32_bf16 v[74:77], v[134:137], v[204:207], v[74:77]
	v_mfma_f32_16x16x32_bf16 v[10:13], v[142:145], v[204:207], v[10:13]
	v_mfma_f32_16x16x32_bf16 v[82:85], v[134:137], v[212:215], v[82:85]
	v_mfma_f32_16x16x32_bf16 v[26:29], v[142:145], v[212:215], v[26:29]
	s_setprio 0
	s_setprio 1
	v_mfma_f32_16x16x32_bf16 v[78:81], v[146:149], v[162:165], v[78:81]
	v_mfma_f32_16x16x32_bf16 v[14:17], v[154:157], v[162:165], v[14:17]
	v_mfma_f32_16x16x32_bf16 v[70:73], v[146:149], v[192:195], v[70:73]
	v_mfma_f32_16x16x32_bf16 v[6:9], v[154:157], v[192:195], v[6:9]
	v_mfma_f32_16x16x32_bf16 v[66:69], v[146:149], v[200:203], v[66:69]
	v_mfma_f32_16x16x32_bf16 v[2:5], v[154:157], v[200:203], v[2:5]
	v_mfma_f32_16x16x32_bf16 v[58:61], v[146:149], v[208:211], v[58:61]
	v_mfma_f32_16x16x32_bf16 v[30:33], v[154:157], v[208:211], v[30:33]
	v_mfma_f32_16x16x32_bf16 v[78:81], v[150:153], v[188:191], v[78:81]
	v_mfma_f32_16x16x32_bf16 v[14:17], v[158:161], v[188:191], v[14:17]
	v_mfma_f32_16x16x32_bf16 v[70:73], v[150:153], v[196:199], v[70:73]
	v_mfma_f32_16x16x32_bf16 v[6:9], v[158:161], v[196:199], v[6:9]
	v_mfma_f32_16x16x32_bf16 v[66:69], v[150:153], v[204:207], v[66:69]
	v_mfma_f32_16x16x32_bf16 v[2:5], v[158:161], v[204:207], v[2:5]
	v_mfma_f32_16x16x32_bf16 v[58:61], v[150:153], v[212:215], v[58:61]
	v_mfma_f32_16x16x32_bf16 v[30:33], v[158:161], v[212:215], v[30:33]
	s_setprio 0
	s_barrier
	s_add_i32 s53, s53, 2
	s_add_u32 s42, s42, 0x100
	s_addc_u32 s43, s43, 0
	s_add_u32 s50, s50, 0x100
	s_addc_u32 s51, s51, 0
	s_cmp_gt_u32 s53, 13
	s_cbranch_scc0 .LBB0_1065
	s_mov_b32 s101, 1
	s_and_b64 vcc, exec, s[24:25]
	s_cbranch_vccz .LBB0_1068
	s_barrier

; #define PG8_STAGE(bufoff, gbase, voff) do { _Pragma("unroll") for (int _i = 0; _i < 2; ++_i) \
;         __builtin_amdgcn_global_load_lds((const unsigned*)((const char*)(gbase) + (voff)[_i]), (LAS unsigned*)(lds + (bufoff) + ldsw + _i * 8192), 16, 0, 0); } while (0)
; #define PG8_LDA(dst, b, h) do { _Pragma("unroll") for (int m = 0; m < 4; ++m) _Pragma("unroll") for (int k = 0; k < 2; ++k) dst[m][k] = *(const LAS bf16x8*)(lds + PG8_SA(b, h) + aoff + m * 2048 + k * 1024); } while (0)
; #define PG8_MMA(ai, bj, At, Bt) do { __builtin_amdgcn_s_setprio(1); _Pragma("unroll") for (int m = 0; m < 4; ++m) _Pragma("unroll") for (int n = 0; n < 2; ++n) _Pragma("unroll") for (int k = 0; k < 2; ++k) \
;         acc[ai][bj][m][n] = __builtin_amdgcn_mfma_f32_16x16x32_bf16(Bt[n][k], At[m][k], acc[ai][bj][m][n], 0, 0, 0); __builtin_amdgcn_s_setprio(0); } while (0)
; #define PG8_WAIT_V(n) asm volatile("s_waitcnt vmcnt(" #n ")" ::: "memory")
; #define PG8_WAIT_L(n) asm volatile("s_waitcnt lgkmcnt(" #n ")" ::: "memory")
; #define PG8_BAR __builtin_amdgcn_s_barrier()
; #define PG8_SCHED __builtin_amdgcn_sched_barrier(0)
; template <class Epi, class Sched, int NSEG, int KK, int LDA, int LDB>
; __device__ __forceinline__ void gemm_phase(LAS unsigned char* lds, const Gemm g, const Sched& S, const Epi& E) {
;     ...
;             PG8_WAIT_V(8); PG8_WAIT_L(0); PG8_BAR; PG8_MMA(0, 0, At, B0); PG8_MMA(0, 1, At, B1); PG8_BAR; PG8_SCHED;
;             PG8_LDA(At, 0, 1); PG8_STAGE(PG8_SB(0, 0), b2, voffB); PG8_STAGE(PG8_SB(0, 1), b2 + hstepB, voffB); PG8_STAGE(PG8_SA(0, 0), a2, voffA);
;             PG8_WAIT_V(8); PG8_WAIT_L(0); PG8_BAR; PG8_MMA(1, 0, At, B0); PG8_MMA(1, 1, At, B1); PG8_BAR; PG8_SCHED;
.Lskw_5_1:
	s_waitcnt lgkmcnt(0)
	s_barrier
	s_setprio 1
	v_mfma_f32_16x16x32_bf16 v[126:129], v[136:139], v[180:183], v[126:129]
	v_mfma_f32_16x16x32_bf16 v[122:125], v[144:147], v[180:183], v[122:125]
	v_mfma_f32_16x16x32_bf16 v[110:113], v[136:139], v[188:191], v[110:113]
	v_mfma_f32_16x16x32_bf16 v[106:109], v[144:147], v[188:191], v[106:109]
	v_mfma_f32_16x16x32_bf16 v[94:97], v[136:139], v[196:199], v[94:97]
	v_mfma_f32_16x16x32_bf16 v[90:93], v[144:147], v[196:199], v[90:93]
	v_mfma_f32_16x16x32_bf16 v[78:81], v[136:139], v[204:207], v[78:81]
	v_mfma_f32_16x16x32_bf16 v[74:77], v[144:147], v[204:207], v[74:77]
	v_mfma_f32_16x16x32_bf16 v[126:129], v[140:143], v[184:187], v[126:129]
	v_mfma_f32_16x16x32_bf16 v[122:125], v[148:151], v[184:187], v[122:125]
	v_mfma_f32_16x16x32_bf16 v[110:113], v[140:143], v[192:195], v[110:113]
	v_mfma_f32_16x16x32_bf16 v[106:109], v[148:151], v[192:195], v[106:109]
	v_mfma_f32_16x16x32_bf16 v[94:97], v[140:143], v[200:203], v[94:97]
	v_mfma_f32_16x16x32_bf16 v[90:93], v[148:151], v[200:203], v[90:93]
	v_mfma_f32_16x16x32_bf16 v[78:81], v[140:143], v[208:211], v[78:81]
	v_mfma_f32_16x16x32_bf16 v[74:77], v[148:151], v[208:211], v[74:77]
	s_setprio 0
	s_setprio 1
	v_mfma_f32_16x16x32_bf16 v[118:121], v[152:155], v[180:183], v[118:121]
	v_mfma_f32_16x16x32_bf16 v[114:117], v[160:163], v[180:183], v[114:117]
	v_mfma_f32_16x16x32_bf16 v[102:105], v[152:155], v[188:191], v[102:105]
	v_mfma_f32_16x16x32_bf16 v[98:101], v[160:163], v[188:191], v[98:101]
	v_mfma_f32_16x16x32_bf16 v[86:89], v[152:155], v[196:199], v[86:89]
	v_mfma_f32_16x16x32_bf16 v[82:85], v[160:163], v[196:199], v[82:85]
	v_mfma_f32_16x16x32_bf16 v[70:73], v[152:155], v[204:207], v[70:73]
	v_mfma_f32_16x16x32_bf16 v[66:69], v[160:163], v[204:207], v[66:69]
	v_mfma_f32_16x16x32_bf16 v[118:121], v[156:159], v[184:187], v[118:121]
	v_mfma_f32_16x16x32_bf16 v[114:117], v[176:179], v[184:187], v[114:117]
	v_mfma_f32_16x16x32_bf16 v[102:105], v[156:159], v[192:195], v[102:105]
	v_mfma_f32_16x16x32_bf16 v[98:101], v[176:179], v[192:195], v[98:101]
	v_mfma_f32_16x16x32_bf16 v[86:89], v[156:159], v[200:203], v[86:89]
	v_mfma_f32_16x16x32_bf16 v[82:85], v[176:179], v[200:203], v[82:85]
	v_mfma_f32_16x16x32_bf16 v[70:73], v[156:159], v[208:211], v[70:73]
	v_mfma_f32_16x16x32_bf16 v[66:69], v[176:179], v[208:211], v[66:69]
	s_setprio 0
	s_barrier
	s_add_i32 s42, s61, s13
	v_lshl_add_u64 v[166:167], s[10:11], 0, v[0:1]
	s_mov_b32 m0, s42
	ds_read_b128 v[180:183], v165 offset:16384
	ds_read_b128 v[184:187], v165 offset:17408
	ds_read_b128 v[188:191], v165 offset:18432
	ds_read_b128 v[192:195], v165 offset:19456
	ds_read_b128 v[196:199], v165 offset:20480
	ds_read_b128 v[200:203], v165 offset:21504
	ds_read_b128 v[204:207], v165 offset:22528
	ds_read_b128 v[208:211], v165 offset:23552
	global_load_lds_dwordx4 v[166:167], off
	s_add_i32 m0, s42, 0x2000
	s_add_u32 s42, s10, 0xb0000
	v_lshl_add_u64 v[172:173], s[10:11], 0, v[130:131]
	s_addc_u32 s43, s11, 0
	s_add_i32 s61, s62, s13
	global_load_lds_dwordx4 v[172:173], off
	v_lshl_add_u64 v[212:213], s[42:43], 0, v[0:1]
	s_mov_b32 m0, s61
	v_lshl_add_u64 v[214:215], s[46:47], 0, v[130:131]
	global_load_lds_dwordx4 v[212:213], off
	v_lshl_add_u64 v[212:213], s[42:43], 0, v[130:131]
	s_add_i32 m0, s61, 0x2000
	s_nop 0
	global_load_lds_dwordx4 v[212:213], off
	v_lshl_add_u64 v[212:213], s[46:47], 0, v[0:1]
	s_mov_b32 m0, s48
	s_nop 0
	global_load_lds_dwordx4 v[212:213], off
	s_mov_b32 m0, s49
	s_nop 0
	global_load_lds_dwordx4 v[214:215], off
	s_cmp_lg_u32 s101, 0
	s_cbranch_scc1 .Lskw_5_2
	s_waitcnt vmcnt(8)
.Lskw_5_2:
	s_mov_b32 s101, 0
	s_waitcnt lgkmcnt(0)
	s_barrier
	s_setprio 1
	v_mfma_f32_16x16x32_bf16 v[62:65], v[136:139], v[180:183], v[62:65]
	v_mfma_f32_16x16x32_bf16 v[58:61], v[144:147], v[180:183], v[58:61]
	v_mfma_f32_16x16x32_bf16 v[46:49], v[136:139], v[188:191], v[46:49]
	v_mfma_f32_16x16x32_bf16 v[42:45], v[144:147], v[188:191], v[42:45]
	v_mfma_f32_16x16x32_bf16 v[30:33], v[136:139], v[196:199], v[30:33]
	v_mfma_f32_16x16x32_bf16 v[26:29], v[144:147], v[196:199], v[26:29]
	v_mfma_f32_16x16x32_bf16 v[14:17], v[136:139], v[204:207], v[14:17]
	v_mfma_f32_16x16x32_bf16 v[10:13], v[144:147], v[204:207], v[10:13]
	v_mfma_f32_16x16x32_bf16 v[62:65], v[140:143], v[184:187], v[62:65]
	v_mfma_f32_16x16x32_bf16 v[58:61], v[148:151], v[184:187], v[58:61]
	v_mfma_f32_16x16x32_bf16 v[46:49], v[140:143], v[192:195], v[46:49]
	v_mfma_f32_16x16x32_bf16 v[42:45], v[148:151], v[192:195], v[42:45]
	v_mfma_f32_16x16x32_bf16 v[30:33], v[140:143], v[200:203], v[30:33]
	v_mfma_f32_16x16x32_bf16 v[26:29], v[148:151], v[200:203], v[26:29]
	v_mfma_f32_16x16x32_bf16 v[14:17], v[140:143], v[208:211], v[14:17]
	v_mfma_f32_16x16x32_bf16 v[10:13], v[148:151], v[208:211], v[10:13]
	s_setprio 0
	s_setprio 1
	v_mfma_f32_16x16x32_bf16 v[54:57], v[152:155], v[180:183], v[54:57]
	v_mfma_f32_16x16x32_bf16 v[50:53], v[160:163], v[180:183], v[50:53]
	v_mfma_f32_16x16x32_bf16 v[38:41], v[152:155], v[188:191], v[38:41]
	v_mfma_f32_16x16x32_bf16 v[34:37], v[160:163], v[188:191], v[34:37]
	v_mfma_f32_16x16x32_bf16 v[22:25], v[152:155], v[196:199], v[22:25]
	v_mfma_f32_16x16x32_bf16 v[18:21], v[160:163], v[196:199], v[18:21]
	v_mfma_f32_16x16x32_bf16 v[6:9], v[152:155], v[204:207], v[6:9]
	v_mfma_f32_16x16x32_bf16 v[2:5], v[160:163], v[204:207], v[2:5]
	v_mfma_f32_16x16x32_bf16 v[54:57], v[156:159], v[184:187], v[54:57]
	v_mfma_f32_16x16x32_bf16 v[50:53], v[176:179], v[184:187], v[50:53]
	v_mfma_f32_16x16x32_bf16 v[38:41], v[156:159], v[192:195], v[38:41]
	v_mfma_f32_16x16x32_bf16 v[34:37], v[176:179], v[192:195], v[34:37]
	v_mfma_f32_16x16x32_bf16 v[22:25], v[156:159], v[200:203], v[22:25]
	v_mfma_f32_16x16x32_bf16 v[18:21], v[176:179], v[200:203], v[18:21]
	v_mfma_f32_16x16x32_bf16 v[6:9], v[156:159], v[208:211], v[6:9]
	v_mfma_f32_16x16x32_bf16 v[2:5], v[176:179], v[208:211], v[2:5]
	s_setprio 0
	s_barrier
; #define PG8_STAGE(bufoff, gbase, voff) do { _Pragma("unroll") for (int _i = 0; _i < 2; ++_i) \
;         __builtin_amdgcn_global_load_lds((const unsigned*)((const char*)(gbase) + (voff)[_i]), (LAS unsigned*)(lds + (bufoff) + ldsw + _i * 8192), 16, 0, 0); } while (0)
; #define PG8_LDA(dst, b, h) do { _Pragma("unroll") for (int m = 0; m < 4; ++m) _Pragma("unroll") for (int k = 0; k < 2; ++k) dst[m][k] = *(const LAS bf16x8*)(lds + PG8_SA(b, h) + aoff + m * 2048 + k * 1024); } while (0)
; #define PG8_LDB(dst, b, h) do { _Pragma("unroll") for (int n = 0; n < 2; ++n) _Pragma("unroll") for (int k = 0; k < 2; ++k) dst[n][k] = *(const LAS bf16x8*)(lds + PG8_SB(b, h) + boff + n * 2048 + k * 1024); } while (0)
; #define PG8_MMA(ai, bj, At, Bt) do { __builtin_amdgcn_s_setprio(1); _Pragma("unroll") for (int m = 0; m < 4; ++m) _Pragma("unroll") for (int n = 0; n < 2; ++n) _Pragma("unroll") for (int k = 0; k < 2; ++k) \
;         acc[ai][bj][m][n] = __builtin_amdgcn_mfma_f32_16x16x32_bf16(Bt[n][k], At[m][k], acc[ai][bj][m][n], 0, 0, 0); __builtin_amdgcn_s_setprio(0); } while (0)
; #define PG8_WAIT_V(n) asm volatile("s_waitcnt vmcnt(" #n ")" ::: "memory")
; #define PG8_WAIT_L(n) asm volatile("s_waitcnt lgkmcnt(" #n ")" ::: "memory")
; #define PG8_BAR __builtin_amdgcn_s_barrier()
; #define PG8_SCHED __builtin_amdgcn_sched_barrier(0)
; template <class Epi, class Sched, int NSEG, int KK, int LDA, int LDB>
; __device__ __forceinline__ void gemm_phase(LAS unsigned char* lds, const Gemm g, const Sched& S, const Epi& E) {
;     ...
;             PG8_LDB(B0, 1, 0); PG8_LDB(B1, 1, 1); PG8_SCHED; PG8_LDA(At, 1, 0); PG8_STAGE(PG8_SA(0, 1), a2 + hstepA, voffA);
;             PG8_WAIT_V(8); PG8_WAIT_L(0); PG8_BAR; PG8_MMA(0, 0, At, B0); PG8_MMA(0, 1, At, B1); PG8_BAR; PG8_SCHED;
	s_add_i32 s61, 0, 0x18000
	s_add_i32 s62, 0, 0x1c000
	v_add_u32_e32 v148, s61, v164
	v_add_u32_e32 v176, s62, v164
	ds_read_b128 v[136:139], v148
	ds_read_b128 v[140:143], v148 offset:1024
	ds_read_b128 v[144:147], v148 offset:256
	ds_read_b128 v[148:151], v148 offset:1280
	ds_read_b128 v[152:155], v176
	ds_read_b128 v[156:159], v176 offset:1024
	ds_read_b128 v[160:163], v176 offset:256
	ds_read_b128 v[176:179], v176 offset:1280
	s_add_u32 s42, s46, 0xb0000
	s_addc_u32 s43, s47, 0
	s_mov_b32 m0, s50
	v_lshl_add_u64 v[216:217], s[42:43], 0, v[0:1]
	ds_read_b128 v[180:183], v165 offset:32768
	ds_read_b128 v[184:187], v165 offset:33792
	ds_read_b128 v[188:191], v165 offset:34816
	ds_read_b128 v[192:195], v165 offset:35840
	ds_read_b128 v[196:199], v165 offset:36864
	ds_read_b128 v[200:203], v165 offset:37888
	ds_read_b128 v[204:207], v165 offset:38912
	ds_read_b128 v[208:211], v165 offset:39936
	global_load_lds_dwordx4 v[216:217], off
	v_lshl_add_u64 v[216:217], s[42:43], 0, v[130:131]
	s_mov_b32 m0, s51
	s_nop 0
	global_load_lds_dwordx4 v[216:217], off
	s_waitcnt vmcnt(8)
	s_waitcnt lgkmcnt(0)
	s_barrier
	s_setprio 1
	v_mfma_f32_16x16x32_bf16 v[126:129], v[136:139], v[180:183], v[126:129]
	v_mfma_f32_16x16x32_bf16 v[122:125], v[144:147], v[180:183], v[122:125]
	v_mfma_f32_16x16x32_bf16 v[110:113], v[136:139], v[188:191], v[110:113]
	v_mfma_f32_16x16x32_bf16 v[106:109], v[144:147], v[188:191], v[106:109]
	v_mfma_f32_16x16x32_bf16 v[94:97], v[136:139], v[196:199], v[94:97]
	v_mfma_f32_16x16x32_bf16 v[90:93], v[144:147], v[196:199], v[90:93]
	v_mfma_f32_16x16x32_bf16 v[78:81], v[136:139], v[204:207], v[78:81]
	v_mfma_f32_16x16x32_bf16 v[74:77], v[144:147], v[204:207], v[74:77]
	v_mfma_f32_16x16x32_bf16 v[126:129], v[140:143], v[184:187], v[126:129]
	v_mfma_f32_16x16x32_bf16 v[122:125], v[148:151], v[184:187], v[122:125]
	v_mfma_f32_16x16x32_bf16 v[110:113], v[140:143], v[192:195], v[110:113]
	v_mfma_f32_16x16x32_bf16 v[106:109], v[148:151], v[192:195], v[106:109]
	v_mfma_f32_16x16x32_bf16 v[94:97], v[140:143], v[200:203], v[94:97]
	v_mfma_f32_16x16x32_bf16 v[90:93], v[148:151], v[200:203], v[90:93]
	v_mfma_f32_16x16x32_bf16 v[78:81], v[140:143], v[208:211], v[78:81]
	v_mfma_f32_16x16x32_bf16 v[74:77], v[148:151], v[208:211], v[74:77]
	s_setprio 0
	s_setprio 1
	v_mfma_f32_16x16x32_bf16 v[118:121], v[152:155], v[180:183], v[118:121]
	v_mfma_f32_16x16x32_bf16 v[114:117], v[160:163], v[180:183], v[114:117]
	v_mfma_f32_16x16x32_bf16 v[102:105], v[152:155], v[188:191], v[102:105]
	v_mfma_f32_16x16x32_bf16 v[98:101], v[160:163], v[188:191], v[98:101]
	v_mfma_f32_16x16x32_bf16 v[86:89], v[152:155], v[196:199], v[86:89]
	v_mfma_f32_16x16x32_bf16 v[82:85], v[160:163], v[196:199], v[82:85]
	v_mfma_f32_16x16x32_bf16 v[70:73], v[152:155], v[204:207], v[70:73]
	v_mfma_f32_16x16x32_bf16 v[66:69], v[160:163], v[204:207], v[66:69]
	v_mfma_f32_16x16x32_bf16 v[118:121], v[156:159], v[184:187], v[118:121]
	v_mfma_f32_16x16x32_bf16 v[114:117], v[176:179], v[184:187], v[114:117]
	v_mfma_f32_16x16x32_bf16 v[102:105], v[156:159], v[192:195], v[102:105]
	v_mfma_f32_16x16x32_bf16 v[98:101], v[176:179], v[192:195], v[98:101]
	v_mfma_f32_16x16x32_bf16 v[86:89], v[156:159], v[200:203], v[86:89]
	v_mfma_f32_16x16x32_bf16 v[82:85], v[176:179], v[200:203], v[82:85]
	v_mfma_f32_16x16x32_bf16 v[70:73], v[156:159], v[208:211], v[70:73]
	v_mfma_f32_16x16x32_bf16 v[66:69], v[176:179], v[208:211], v[66:69]
	s_setprio 0
	s_barrier
; #define PG8_STAGE(bufoff, gbase, voff) do { _Pragma("unroll") for (int _i = 0; _i < 2; ++_i) \
;         __builtin_amdgcn_global_load_lds((const unsigned*)((const char*)(gbase) + (voff)[_i]), (LAS unsigned*)(lds + (bufoff) + ldsw + _i * 8192), 16, 0, 0); } while (0)
; #define PG8_LDA(dst, b, h) do { _Pragma("unroll") for (int m = 0; m < 4; ++m) _Pragma("unroll") for (int k = 0; k < 2; ++k) dst[m][k] = *(const LAS bf16x8*)(lds + PG8_SA(b, h) + aoff + m * 2048 + k * 1024); } while (0)
; #define PG8_MMA(ai, bj, At, Bt) do { __builtin_amdgcn_s_setprio(1); _Pragma("unroll") for (int m = 0; m < 4; ++m) _Pragma("unroll") for (int n = 0; n < 2; ++n) _Pragma("unroll") for (int k = 0; k < 2; ++k) \
;         acc[ai][bj][m][n] = __builtin_amdgcn_mfma_f32_16x16x32_bf16(Bt[n][k], At[m][k], acc[ai][bj][m][n], 0, 0, 0); __builtin_amdgcn_s_setprio(0); } while (0)
; #define PG8_WAIT_V(n) asm volatile("s_waitcnt vmcnt(" #n ")" ::: "memory")
; #define PG8_WAIT_L(n) asm volatile("s_waitcnt lgkmcnt(" #n ")" ::: "memory")
; #define PG8_BAR __builtin_amdgcn_s_barrier()
; #define PG8_SCHED __builtin_amdgcn_sched_barrier(0)
; template <class Epi, class Sched, int NSEG, int KK, int LDA, int LDB>
; __device__ __forceinline__ void gemm_phase(LAS unsigned char* lds, const Gemm g, const Sched& S, const Epi& E) {
;     ...
;             PG8_LDA(At, 1, 1); PG8_STAGE(PG8_SB(1, 0), b3, voffB); PG8_STAGE(PG8_SB(1, 1), b3 + hstepB, voffB); PG8_STAGE(PG8_SA(1, 0), a3, voffA);
;             PG8_WAIT_V(8); PG8_WAIT_L(0); PG8_BAR; PG8_MMA(1, 0, At, B0); PG8_MMA(1, 1, At, B1); PG8_BAR; PG8_SCHED;
;         }
;         if (wr == 0) PG8_BAR;
	s_add_i32 s42, s61, s13
	v_lshl_add_u64 v[166:167], v[166:167], 0, s[28:29]
	s_mov_b32 m0, s42
	ds_read_b128 v[180:183], v165 offset:49152
	ds_read_b128 v[184:187], v165 offset:50176
	ds_read_b128 v[188:191], v165 offset:51200
	ds_read_b128 v[192:195], v165 offset:52224
	ds_read_b128 v[196:199], v165 offset:53248
	ds_read_b128 v[200:203], v165 offset:54272
	ds_read_b128 v[204:207], v165 offset:55296
	ds_read_b128 v[208:211], v165 offset:56320
	global_load_lds_dwordx4 v[166:167], off
	s_add_i32 m0, s42, 0x2000
	s_add_u32 s10, s10, 0xb0080
	v_lshl_add_u64 v[166:167], v[172:173], 0, s[28:29]
	s_addc_u32 s11, s11, 0
	s_add_i32 s42, s62, s13
	global_load_lds_dwordx4 v[166:167], off
	v_lshl_add_u64 v[166:167], s[10:11], 0, v[0:1]
	s_mov_b32 m0, s42
	s_nop 0
	global_load_lds_dwordx4 v[166:167], off
	v_lshl_add_u64 v[166:167], s[10:11], 0, v[130:131]
	s_add_i32 m0, s42, 0x2000
	s_nop 0
	global_load_lds_dwordx4 v[166:167], off
	v_lshl_add_u64 v[166:167], v[212:213], 0, s[28:29]
	s_mov_b32 m0, s53
	s_nop 0
	global_load_lds_dwordx4 v[166:167], off
	v_lshl_add_u64 v[166:167], v[214:215], 0, s[28:29]
	s_mov_b32 m0, s54
	s_nop 0
	global_load_lds_dwordx4 v[166:167], off
	s_waitcnt vmcnt(8)
	s_waitcnt lgkmcnt(0)
	s_barrier
	s_setprio 1
	v_mfma_f32_16x16x32_bf16 v[62:65], v[136:139], v[180:183], v[62:65]
	v_mfma_f32_16x16x32_bf16 v[58:61], v[144:147], v[180:183], v[58:61]
	v_mfma_f32_16x16x32_bf16 v[46:49], v[136:139], v[188:191], v[46:49]
	v_mfma_f32_16x16x32_bf16 v[42:45], v[144:147], v[188:191], v[42:45]
	v_mfma_f32_16x16x32_bf16 v[30:33], v[136:139], v[196:199], v[30:33]
	v_mfma_f32_16x16x32_bf16 v[26:29], v[144:147], v[196:199], v[26:29]
	v_mfma_f32_16x16x32_bf16 v[14:17], v[136:139], v[204:207], v[14:17]
	v_mfma_f32_16x16x32_bf16 v[10:13], v[144:147], v[204:207], v[10:13]
	v_mfma_f32_16x16x32_bf16 v[62:65], v[140:143], v[184:187], v[62:65]
	v_mfma_f32_16x16x32_bf16 v[58:61], v[148:151], v[184:187], v[58:61]
	v_mfma_f32_16x16x32_bf16 v[46:49], v[140:143], v[192:195], v[46:49]
	v_mfma_f32_16x16x32_bf16 v[42:45], v[148:151], v[192:195], v[42:45]
	v_mfma_f32_16x16x32_bf16 v[30:33], v[140:143], v[200:203], v[30:33]
	v_mfma_f32_16x16x32_bf16 v[26:29], v[148:151], v[200:203], v[26:29]
	v_mfma_f32_16x16x32_bf16 v[14:17], v[140:143], v[208:211], v[14:17]
	v_mfma_f32_16x16x32_bf16 v[10:13], v[148:151], v[208:211], v[10:13]
	s_setprio 0
	s_setprio 1
	v_mfma_f32_16x16x32_bf16 v[54:57], v[152:155], v[180:183], v[54:57]
	v_mfma_f32_16x16x32_bf16 v[50:53], v[160:163], v[180:183], v[50:53]
	v_mfma_f32_16x16x32_bf16 v[38:41], v[152:155], v[188:191], v[38:41]
	v_mfma_f32_16x16x32_bf16 v[34:37], v[160:163], v[188:191], v[34:37]
	v_mfma_f32_16x16x32_bf16 v[22:25], v[152:155], v[196:199], v[22:25]
	v_mfma_f32_16x16x32_bf16 v[18:21], v[160:163], v[196:199], v[18:21]
	v_mfma_f32_16x16x32_bf16 v[6:9], v[152:155], v[204:207], v[6:9]
	v_mfma_f32_16x16x32_bf16 v[2:5], v[160:163], v[204:207], v[2:5]
	v_mfma_f32_16x16x32_bf16 v[54:57], v[156:159], v[184:187], v[54:57]
	v_mfma_f32_16x16x32_bf16 v[50:53], v[176:179], v[184:187], v[50:53]
	v_mfma_f32_16x16x32_bf16 v[38:41], v[156:159], v[192:195], v[38:41]
	v_mfma_f32_16x16x32_bf16 v[34:37], v[176:179], v[192:195], v[34:37]
	v_mfma_f32_16x16x32_bf16 v[22:25], v[156:159], v[200:203], v[22:25]
	v_mfma_f32_16x16x32_bf16 v[18:21], v[176:179], v[200:203], v[18:21]
	v_mfma_f32_16x16x32_bf16 v[6:9], v[156:159], v[208:211], v[6:9]
	v_mfma_f32_16x16x32_bf16 v[2:5], v[176:179], v[208:211], v[2:5]
	s_setprio 0
	s_barrier
	s_add_i32 s60, s60, 2
	s_add_u32 s58, s58, 0x100
	s_addc_u32 s59, s59, 0
	s_cmp_gt_u32 s60, 41
	s_mov_b64 s[42:43], s[40:41]
	s_cbranch_scc0 .LBB0_1258
	s_mov_b32 s101, 1
	s_and_b64 vcc, exec, s[8:9]
	s_cbranch_vccz .LBB0_1261
	s_barrier
